# redundant s_waitcnt lgkmcnt(0) at the head of each GEMM MFMA segment removed (already waited in front of the barrier)
# speedup vs baseline: 1.0036x; 1.0036x over previous
; #define PG8_STAGE(bufoff, gbase, voff) do { _Pragma("unroll") for (int _i = 0; _i < 2; ++_i) \
;         __builtin_amdgcn_global_load_lds((const unsigned*)((const char*)(gbase) + (voff)[_i]), (PG8_LAS unsigned*)(lds + (bufoff) + ldsw + _i * 8192), 16, 0, 0); } while (0)
; #define PG8_LDA(dst, b, h) do { _Pragma("unroll") for (int m = 0; m < 4; ++m) _Pragma("unroll") for (int k = 0; k < 2; ++k) dst[m][k] = *(const PG8_LAS bf16x8*)(lds + PG8_SA(b, h) + aoff + m * 2048 + k * 1024); } while (0)
; #define PG8_LDB(dst, b, h) do { _Pragma("unroll") for (int n = 0; n < 2; ++n) _Pragma("unroll") for (int k = 0; k < 2; ++k) dst[n][k] = *(const PG8_LAS bf16x8*)(lds + PG8_SB(b, h) + boff + n * 2048 + k * 1024); } while (0)
; #define PG8_MMA(ai, bj, At, Bt) do { __builtin_amdgcn_s_setprio(1); _Pragma("unroll") for (int m = 0; m < 4; ++m) _Pragma("unroll") for (int n = 0; n < 2; ++n) _Pragma("unroll") for (int k = 0; k < 2; ++k) \
;         acc[ai][bj][m][n] = __builtin_amdgcn_mfma_f32_16x16x32_bf16(Bt[n][k], At[m][k], acc[ai][bj][m][n], 0, 0, 0); __builtin_amdgcn_s_setprio(0); } while (0)
; #define PG8_WAIT_V(n) asm volatile("s_waitcnt vmcnt(" #n ")" ::: "memory")
; #define PG8_WAIT_L(n) asm volatile("s_waitcnt lgkmcnt(" #n ")" ::: "memory")
; #define PG8_BAR __builtin_amdgcn_s_barrier()
; template <class Epi, class Sched, bool ALIGN_EPI = false, bool SP2 = false>
; __device__ __forceinline__ void gemm_phase(PG8_LAS unsigned char* lds, const Gemm g, const Sched& S, const Epi& E) {
;     ...
;             const char* a1 = cA + (size_t)(t + 1) * kstep;
;             const char* a2 = last ? nA : cA + (size_t)(t + 2) * kstep; const char* b2 = last ? nB : cB + (size_t)(t + 2) * kstep;
;             const char* a3 = a2 + kstep; const char* b3 = b2 + kstep;
;             if (last && has_next) S.a_ready(nxt);
;             if constexpr (SP2) {
;             PG8_LDB(B0, 0, 0); PG8_LDB(B1, 0, 1); PG8_SCHED; PG8_LDA(At, 0, 0); PG8_STAGE(PG8_SA(1, 1), a1 + hstepA, voffA);
;             PG8_WAIT_V(8); PG8_WAIT_L(0); PG8_BAR; PG8_MMA(0, 0, At, B0); PG8_MMA(0, 1, At, B1); PG8_BAR; PG8_SCHED;
;             PG8_LDA(At, 0, 1); PG8_STAGE(PG8_SB(0, 0), b2, voffB); PG8_STAGE(PG8_SB(0, 1), b2 + hstepB, voffB); PG8_STAGE(PG8_SA(0, 0), a2, voffA);
;             PG8_WAIT_V(8); PG8_WAIT_L(0); PG8_BAR; PG8_MMA(1, 0, At, B0); PG8_MMA(1, 1, At, B1); PG8_BAR; PG8_SCHED;
.LBB0_187:
	ds_read_b128 v[128:131], v173
	ds_read_b128 v[132:135], v173 offset:1024
	ds_read_b128 v[152:155], v173 offset:2048
	ds_read_b128 v[156:159], v173 offset:3072
	ds_read_b128 v[160:163], v174
	ds_read_b128 v[164:167], v174 offset:1024
	ds_read_b128 v[180:183], v174 offset:2048
	ds_read_b128 v[184:187], v174 offset:3072
	s_add_u32 s16, s12, 0xfff80080
	s_addc_u32 s17, s13, -1
	s_cmp_eq_u32 s61, 28
	s_cselect_b32 s19, s1, s17
	s_cselect_b32 s18, s26, s16
	s_cselect_b32 s17, s15, s60
	s_cselect_b32 s16, s36, s37
	ds_read_b128 v[188:191], v175
	ds_read_b128 v[192:195], v175 offset:1024
	ds_read_b128 v[196:199], v175 offset:2048
	ds_read_b128 v[200:203], v175 offset:3072
	ds_read_b128 v[204:207], v175 offset:4096
	ds_read_b128 v[208:211], v175 offset:5120
	ds_read_b128 v[212:215], v175 offset:6144
	ds_read_b128 v[216:219], v175 offset:7168
	s_add_u32 s98, s12, 0xfff80000
	s_addc_u32 s99, s13, -1
	s_mov_b32 m0, s7
	s_nop 0
	global_load_lds_dwordx4 v136, s[98:99]
	s_mov_b32 m0, s46
	s_nop 0
	global_load_lds_dwordx4 v140, s[98:99]
	s_add_i32 m0, s77, 0xc000
	s_nop 0
	global_load_lds_dwordx4 v144, s[12:13]
	s_add_i32 m0, s77, 0xe000
	s_nop 0
	global_load_lds_dwordx4 v146, s[12:13]
	s_waitcnt vmcnt(8)
	s_waitcnt lgkmcnt(0)
	s_barrier
	s_setprio 1
	v_mfma_f32_16x16x32_bf16 v[124:127], v[128:131], v[188:191], v[124:127]
	v_mfma_f32_16x16x32_bf16 v[120:123], v[152:155], v[188:191], v[120:123]
	v_mfma_f32_16x16x32_bf16 v[108:111], v[128:131], v[196:199], v[108:111]
	v_mfma_f32_16x16x32_bf16 v[104:107], v[152:155], v[196:199], v[104:107]
	v_mfma_f32_16x16x32_bf16 v[92:95], v[128:131], v[204:207], v[92:95]
	v_mfma_f32_16x16x32_bf16 v[88:91], v[152:155], v[204:207], v[88:91]
	v_mfma_f32_16x16x32_bf16 v[76:79], v[128:131], v[212:215], v[76:79]
	v_mfma_f32_16x16x32_bf16 v[72:75], v[152:155], v[212:215], v[72:75]
	v_mfma_f32_16x16x32_bf16 v[124:127], v[132:135], v[192:195], v[124:127]
	v_mfma_f32_16x16x32_bf16 v[120:123], v[156:159], v[192:195], v[120:123]
	v_mfma_f32_16x16x32_bf16 v[108:111], v[132:135], v[200:203], v[108:111]
	v_mfma_f32_16x16x32_bf16 v[104:107], v[156:159], v[200:203], v[104:107]
	v_mfma_f32_16x16x32_bf16 v[92:95], v[132:135], v[208:211], v[92:95]
	v_mfma_f32_16x16x32_bf16 v[88:91], v[156:159], v[208:211], v[88:91]
	v_mfma_f32_16x16x32_bf16 v[76:79], v[132:135], v[216:219], v[76:79]
	v_mfma_f32_16x16x32_bf16 v[72:75], v[156:159], v[216:219], v[72:75]
	s_setprio 0
	s_setprio 1
	v_mfma_f32_16x16x32_bf16 v[116:119], v[160:163], v[188:191], v[116:119]
	v_mfma_f32_16x16x32_bf16 v[112:115], v[180:183], v[188:191], v[112:115]
	v_mfma_f32_16x16x32_bf16 v[100:103], v[160:163], v[196:199], v[100:103]
	v_mfma_f32_16x16x32_bf16 v[96:99], v[180:183], v[196:199], v[96:99]
	v_mfma_f32_16x16x32_bf16 v[84:87], v[160:163], v[204:207], v[84:87]
	v_mfma_f32_16x16x32_bf16 v[80:83], v[180:183], v[204:207], v[80:83]
	v_mfma_f32_16x16x32_bf16 v[68:71], v[160:163], v[212:215], v[68:71]
	v_mfma_f32_16x16x32_bf16 v[64:67], v[180:183], v[212:215], v[64:67]
	v_mfma_f32_16x16x32_bf16 v[116:119], v[164:167], v[192:195], v[116:119]
	v_mfma_f32_16x16x32_bf16 v[112:115], v[184:187], v[192:195], v[112:115]
	v_mfma_f32_16x16x32_bf16 v[100:103], v[164:167], v[200:203], v[100:103]
	v_mfma_f32_16x16x32_bf16 v[96:99], v[184:187], v[200:203], v[96:99]
	v_mfma_f32_16x16x32_bf16 v[84:87], v[164:167], v[208:211], v[84:87]
	v_mfma_f32_16x16x32_bf16 v[80:83], v[184:187], v[208:211], v[80:83]
	v_mfma_f32_16x16x32_bf16 v[68:71], v[164:167], v[216:219], v[68:71]
	v_mfma_f32_16x16x32_bf16 v[64:67], v[184:187], v[216:219], v[64:67]
	s_setprio 0
	s_barrier
	s_add_i32 s69, s47, s33
	s_mov_b32 m0, s69
	ds_read_b128 v[188:191], v175 offset:16384
	ds_read_b128 v[192:195], v175 offset:17408
	ds_read_b128 v[196:199], v175 offset:18432
	ds_read_b128 v[200:203], v175 offset:19456
	ds_read_b128 v[204:207], v175 offset:20480
	ds_read_b128 v[208:211], v175 offset:21504
	ds_read_b128 v[212:215], v175 offset:22528
	ds_read_b128 v[216:219], v175 offset:23552
	global_load_lds_dwordx4 v138, s[16:17]
	s_add_i32 m0, s69, 0x2000
	s_add_u32 s70, s16, 0x80000
	s_addc_u32 s71, s17, 0
	s_add_i32 s69, s56, s33
	global_load_lds_dwordx4 v142, s[16:17]
	s_mov_b32 m0, s69
	s_nop 0
	global_load_lds_dwordx4 v138, s[70:71]
	s_add_i32 m0, s69, 0x2000
	s_nop 0
	global_load_lds_dwordx4 v142, s[70:71]
	s_waitcnt vmcnt(6)
	s_waitcnt lgkmcnt(0)
	s_barrier
	s_setprio 1
	v_mfma_f32_16x16x32_bf16 v[60:63], v[128:131], v[188:191], v[60:63]
	v_mfma_f32_16x16x32_bf16 v[56:59], v[152:155], v[188:191], v[56:59]
	v_mfma_f32_16x16x32_bf16 v[44:47], v[128:131], v[196:199], v[44:47]
	v_mfma_f32_16x16x32_bf16 v[40:43], v[152:155], v[196:199], v[40:43]
	v_mfma_f32_16x16x32_bf16 v[28:31], v[128:131], v[204:207], v[28:31]
	v_mfma_f32_16x16x32_bf16 v[24:27], v[152:155], v[204:207], v[24:27]
	v_mfma_f32_16x16x32_bf16 v[12:15], v[128:131], v[212:215], v[12:15]
	v_mfma_f32_16x16x32_bf16 v[8:11], v[152:155], v[212:215], v[8:11]
	v_mfma_f32_16x16x32_bf16 v[60:63], v[132:135], v[192:195], v[60:63]
	v_mfma_f32_16x16x32_bf16 v[56:59], v[156:159], v[192:195], v[56:59]
	v_mfma_f32_16x16x32_bf16 v[44:47], v[132:135], v[200:203], v[44:47]
	v_mfma_f32_16x16x32_bf16 v[40:43], v[156:159], v[200:203], v[40:43]
	v_mfma_f32_16x16x32_bf16 v[28:31], v[132:135], v[208:211], v[28:31]
	v_mfma_f32_16x16x32_bf16 v[24:27], v[156:159], v[208:211], v[24:27]
	v_mfma_f32_16x16x32_bf16 v[12:15], v[132:135], v[216:219], v[12:15]
	v_mfma_f32_16x16x32_bf16 v[8:11], v[156:159], v[216:219], v[8:11]
	s_setprio 0
	s_setprio 1
	v_mfma_f32_16x16x32_bf16 v[52:55], v[160:163], v[188:191], v[52:55]
	v_mfma_f32_16x16x32_bf16 v[48:51], v[180:183], v[188:191], v[48:51]
	v_mfma_f32_16x16x32_bf16 v[36:39], v[160:163], v[196:199], v[36:39]
	v_mfma_f32_16x16x32_bf16 v[32:35], v[180:183], v[196:199], v[32:35]
	v_mfma_f32_16x16x32_bf16 v[20:23], v[160:163], v[204:207], v[20:23]
	v_mfma_f32_16x16x32_bf16 v[16:19], v[180:183], v[204:207], v[16:19]
	v_mfma_f32_16x16x32_bf16 v[4:7], v[160:163], v[212:215], v[4:7]
	v_mfma_f32_16x16x32_bf16 v[0:3], v[180:183], v[212:215], v[0:3]
	v_mfma_f32_16x16x32_bf16 v[52:55], v[164:167], v[192:195], v[52:55]
	v_mfma_f32_16x16x32_bf16 v[48:51], v[184:187], v[192:195], v[48:51]
	v_mfma_f32_16x16x32_bf16 v[36:39], v[164:167], v[200:203], v[36:39]
	v_mfma_f32_16x16x32_bf16 v[32:35], v[184:187], v[200:203], v[32:35]
	v_mfma_f32_16x16x32_bf16 v[20:23], v[164:167], v[208:211], v[20:23]
	v_mfma_f32_16x16x32_bf16 v[16:19], v[184:187], v[208:211], v[16:19]
	v_mfma_f32_16x16x32_bf16 v[4:7], v[164:167], v[216:219], v[4:7]
	v_mfma_f32_16x16x32_bf16 v[0:3], v[184:187], v[216:219], v[0:3]
	s_setprio 0
	s_barrier
; #define PG8_STAGE(bufoff, gbase, voff) do { _Pragma("unroll") for (int _i = 0; _i < 2; ++_i) \
;         __builtin_amdgcn_global_load_lds((const unsigned*)((const char*)(gbase) + (voff)[_i]), (PG8_LAS unsigned*)(lds + (bufoff) + ldsw + _i * 8192), 16, 0, 0); } while (0)
; #define PG8_LDA(dst, b, h) do { _Pragma("unroll") for (int m = 0; m < 4; ++m) _Pragma("unroll") for (int k = 0; k < 2; ++k) dst[m][k] = *(const PG8_LAS bf16x8*)(lds + PG8_SA(b, h) + aoff + m * 2048 + k * 1024); } while (0)
; #define PG8_LDB(dst, b, h) do { _Pragma("unroll") for (int n = 0; n < 2; ++n) _Pragma("unroll") for (int k = 0; k < 2; ++k) dst[n][k] = *(const PG8_LAS bf16x8*)(lds + PG8_SB(b, h) + boff + n * 2048 + k * 1024); } while (0)
; #define PG8_MMA(ai, bj, At, Bt) do { __builtin_amdgcn_s_setprio(1); _Pragma("unroll") for (int m = 0; m < 4; ++m) _Pragma("unroll") for (int n = 0; n < 2; ++n) _Pragma("unroll") for (int k = 0; k < 2; ++k) \
;         acc[ai][bj][m][n] = __builtin_amdgcn_mfma_f32_16x16x32_bf16(Bt[n][k], At[m][k], acc[ai][bj][m][n], 0, 0, 0); __builtin_amdgcn_s_setprio(0); } while (0)
; #define PG8_WAIT_V(n) asm volatile("s_waitcnt vmcnt(" #n ")" ::: "memory")
; #define PG8_WAIT_L(n) asm volatile("s_waitcnt lgkmcnt(" #n ")" ::: "memory")
; #define PG8_BAR __builtin_amdgcn_s_barrier()
; #define PG8_SCHED __builtin_amdgcn_sched_barrier(0)
; template <class Epi, class Sched, bool ALIGN_EPI = false, bool SP2 = false>
; __device__ __forceinline__ void gemm_phase(PG8_LAS unsigned char* lds, const Gemm g, const Sched& S, const Epi& E) {
;     ...
;             PG8_LDB(B0, 1, 0); PG8_LDB(B1, 1, 1); PG8_SCHED; PG8_LDA(At, 1, 0); PG8_STAGE(PG8_SA(0, 1), a2 + hstepA, voffA);
;             PG8_WAIT_V(8); PG8_WAIT_L(0); PG8_BAR; PG8_MMA(0, 0, At, B0); PG8_MMA(0, 1, At, B1); PG8_BAR; PG8_SCHED;
;             PG8_LDA(At, 1, 1); PG8_STAGE(PG8_SB(1, 0), b3, voffB); PG8_STAGE(PG8_SB(1, 1), b3 + hstepB, voffB); PG8_STAGE(PG8_SA(1, 0), a3, voffA);
;             PG8_WAIT_V(8); PG8_WAIT_L(0); PG8_BAR; PG8_MMA(1, 0, At, B0); PG8_MMA(1, 1, At, B1); PG8_BAR; PG8_SCHED;
;     ...
;         if constexpr (ALIGN_EPI) { if (wr == 0) PG8_BAR; }
	s_add_i32 s69, 0, 0x18000
	s_add_i32 s70, 0, 0x1c000
	v_add_u32_e32 v156, s69, v172
	v_add_u32_e32 v179, s70, v172
	ds_read_b128 v[128:131], v156
	ds_read_b128 v[132:135], v156 offset:1024
	ds_read_b128 v[152:155], v156 offset:2048
	ds_read_b128 v[156:159], v156 offset:3072
	ds_read_b128 v[160:163], v179
	ds_read_b128 v[164:167], v179 offset:1024
	ds_read_b128 v[180:183], v179 offset:2048
	ds_read_b128 v[184:187], v179 offset:3072
	s_mov_b64 s[100:101], s[18:19]
	s_add_u32 s18, s18, 0x80000
	s_addc_u32 s19, s19, 0
	ds_read_b128 v[188:191], v175 offset:32768
	ds_read_b128 v[192:195], v175 offset:33792
	ds_read_b128 v[196:199], v175 offset:34816
	ds_read_b128 v[200:203], v175 offset:35840
	ds_read_b128 v[204:207], v175 offset:36864
	ds_read_b128 v[208:211], v175 offset:37888
	ds_read_b128 v[212:215], v175 offset:38912
	ds_read_b128 v[216:219], v175 offset:39936
	s_mov_b32 m0, s77
	s_nop 0
	global_load_lds_dwordx4 v136, s[100:101]
	s_mov_b32 m0, s22
	s_nop 0
	global_load_lds_dwordx4 v140, s[100:101]
	s_mov_b32 m0, s23
	s_nop 0
	global_load_lds_dwordx4 v136, s[18:19]
	s_mov_b32 m0, s4
	s_nop 0
	global_load_lds_dwordx4 v140, s[18:19]
	s_waitcnt vmcnt(8)
	s_waitcnt lgkmcnt(0)
	s_barrier
	s_setprio 1
	v_mfma_f32_16x16x32_bf16 v[124:127], v[128:131], v[188:191], v[124:127]
	v_mfma_f32_16x16x32_bf16 v[120:123], v[152:155], v[188:191], v[120:123]
	v_mfma_f32_16x16x32_bf16 v[108:111], v[128:131], v[196:199], v[108:111]
	v_mfma_f32_16x16x32_bf16 v[104:107], v[152:155], v[196:199], v[104:107]
	v_mfma_f32_16x16x32_bf16 v[92:95], v[128:131], v[204:207], v[92:95]
	v_mfma_f32_16x16x32_bf16 v[88:91], v[152:155], v[204:207], v[88:91]
	v_mfma_f32_16x16x32_bf16 v[76:79], v[128:131], v[212:215], v[76:79]
	v_mfma_f32_16x16x32_bf16 v[72:75], v[152:155], v[212:215], v[72:75]
	v_mfma_f32_16x16x32_bf16 v[124:127], v[132:135], v[192:195], v[124:127]
	v_mfma_f32_16x16x32_bf16 v[120:123], v[156:159], v[192:195], v[120:123]
	v_mfma_f32_16x16x32_bf16 v[108:111], v[132:135], v[200:203], v[108:111]
	v_mfma_f32_16x16x32_bf16 v[104:107], v[156:159], v[200:203], v[104:107]
	v_mfma_f32_16x16x32_bf16 v[92:95], v[132:135], v[208:211], v[92:95]
	v_mfma_f32_16x16x32_bf16 v[88:91], v[156:159], v[208:211], v[88:91]
	v_mfma_f32_16x16x32_bf16 v[76:79], v[132:135], v[216:219], v[76:79]
	v_mfma_f32_16x16x32_bf16 v[72:75], v[156:159], v[216:219], v[72:75]
	s_setprio 0
	s_setprio 1
	v_mfma_f32_16x16x32_bf16 v[116:119], v[160:163], v[188:191], v[116:119]
	v_mfma_f32_16x16x32_bf16 v[112:115], v[180:183], v[188:191], v[112:115]
	v_mfma_f32_16x16x32_bf16 v[100:103], v[160:163], v[196:199], v[100:103]
	v_mfma_f32_16x16x32_bf16 v[96:99], v[180:183], v[196:199], v[96:99]
	v_mfma_f32_16x16x32_bf16 v[84:87], v[160:163], v[204:207], v[84:87]
	v_mfma_f32_16x16x32_bf16 v[80:83], v[180:183], v[204:207], v[80:83]
	v_mfma_f32_16x16x32_bf16 v[68:71], v[160:163], v[212:215], v[68:71]
	v_mfma_f32_16x16x32_bf16 v[64:67], v[180:183], v[212:215], v[64:67]
	v_mfma_f32_16x16x32_bf16 v[116:119], v[164:167], v[192:195], v[116:119]
	v_mfma_f32_16x16x32_bf16 v[112:115], v[184:187], v[192:195], v[112:115]
	v_mfma_f32_16x16x32_bf16 v[100:103], v[164:167], v[200:203], v[100:103]
	v_mfma_f32_16x16x32_bf16 v[96:99], v[184:187], v[200:203], v[96:99]
	v_mfma_f32_16x16x32_bf16 v[84:87], v[164:167], v[208:211], v[84:87]
	v_mfma_f32_16x16x32_bf16 v[80:83], v[184:187], v[208:211], v[80:83]
	v_mfma_f32_16x16x32_bf16 v[68:71], v[164:167], v[216:219], v[68:71]
	v_mfma_f32_16x16x32_bf16 v[64:67], v[184:187], v[216:219], v[64:67]
	s_setprio 0
	s_barrier
	s_add_i32 s18, s69, s33
	s_add_u32 s98, s16, 0x80
	s_addc_u32 s99, s17, 0
	s_mov_b32 m0, s18
	ds_read_b128 v[188:191], v175 offset:49152
	ds_read_b128 v[192:195], v175 offset:50176
	ds_read_b128 v[196:199], v175 offset:51200
	ds_read_b128 v[200:203], v175 offset:52224
	ds_read_b128 v[204:207], v175 offset:53248
	ds_read_b128 v[208:211], v175 offset:54272
	ds_read_b128 v[212:215], v175 offset:55296
	ds_read_b128 v[216:219], v175 offset:56320
	global_load_lds_dwordx4 v138, s[98:99]
	s_add_i32 m0, s18, 0x2000
	s_add_u32 s16, s16, 0x80080
	s_addc_u32 s17, s17, 0
	s_add_i32 s18, s70, s33
	global_load_lds_dwordx4 v142, s[98:99]
	s_mov_b32 m0, s18
	s_nop 0
	global_load_lds_dwordx4 v138, s[16:17]
	s_add_i32 m0, s18, 0x2000
	s_nop 0
	global_load_lds_dwordx4 v142, s[16:17]
	s_waitcnt vmcnt(6)
	s_waitcnt lgkmcnt(0)
	s_barrier
	s_setprio 1
	v_mfma_f32_16x16x32_bf16 v[60:63], v[128:131], v[188:191], v[60:63]
	v_mfma_f32_16x16x32_bf16 v[56:59], v[152:155], v[188:191], v[56:59]
	v_mfma_f32_16x16x32_bf16 v[44:47], v[128:131], v[196:199], v[44:47]
	v_mfma_f32_16x16x32_bf16 v[40:43], v[152:155], v[196:199], v[40:43]
	v_mfma_f32_16x16x32_bf16 v[28:31], v[128:131], v[204:207], v[28:31]
	v_mfma_f32_16x16x32_bf16 v[24:27], v[152:155], v[204:207], v[24:27]
	v_mfma_f32_16x16x32_bf16 v[12:15], v[128:131], v[212:215], v[12:15]
	v_mfma_f32_16x16x32_bf16 v[8:11], v[152:155], v[212:215], v[8:11]
	v_mfma_f32_16x16x32_bf16 v[60:63], v[132:135], v[192:195], v[60:63]
	v_mfma_f32_16x16x32_bf16 v[56:59], v[156:159], v[192:195], v[56:59]
	v_mfma_f32_16x16x32_bf16 v[44:47], v[132:135], v[200:203], v[44:47]
	v_mfma_f32_16x16x32_bf16 v[40:43], v[156:159], v[200:203], v[40:43]
	v_mfma_f32_16x16x32_bf16 v[28:31], v[132:135], v[208:211], v[28:31]
	v_mfma_f32_16x16x32_bf16 v[24:27], v[156:159], v[208:211], v[24:27]
	v_mfma_f32_16x16x32_bf16 v[12:15], v[132:135], v[216:219], v[12:15]
	v_mfma_f32_16x16x32_bf16 v[8:11], v[156:159], v[216:219], v[8:11]
	s_setprio 0
	s_setprio 1
	v_mfma_f32_16x16x32_bf16 v[52:55], v[160:163], v[188:191], v[52:55]
	v_mfma_f32_16x16x32_bf16 v[48:51], v[180:183], v[188:191], v[48:51]
	v_mfma_f32_16x16x32_bf16 v[36:39], v[160:163], v[196:199], v[36:39]
	v_mfma_f32_16x16x32_bf16 v[32:35], v[180:183], v[196:199], v[32:35]
	v_mfma_f32_16x16x32_bf16 v[20:23], v[160:163], v[204:207], v[20:23]
	v_mfma_f32_16x16x32_bf16 v[16:19], v[180:183], v[204:207], v[16:19]
	v_mfma_f32_16x16x32_bf16 v[4:7], v[160:163], v[212:215], v[4:7]
	v_mfma_f32_16x16x32_bf16 v[0:3], v[180:183], v[212:215], v[0:3]
	v_mfma_f32_16x16x32_bf16 v[52:55], v[164:167], v[192:195], v[52:55]
	v_mfma_f32_16x16x32_bf16 v[48:51], v[184:187], v[192:195], v[48:51]
	v_mfma_f32_16x16x32_bf16 v[36:39], v[164:167], v[200:203], v[36:39]
	v_mfma_f32_16x16x32_bf16 v[32:35], v[184:187], v[200:203], v[32:35]
	v_mfma_f32_16x16x32_bf16 v[20:23], v[164:167], v[208:211], v[20:23]
	v_mfma_f32_16x16x32_bf16 v[16:19], v[184:187], v[208:211], v[16:19]
	v_mfma_f32_16x16x32_bf16 v[4:7], v[164:167], v[216:219], v[4:7]
	v_mfma_f32_16x16x32_bf16 v[0:3], v[184:187], v[216:219], v[0:3]
	s_setprio 0
	s_barrier
	s_add_i32 s61, s61, 2
	s_add_u32 s12, s12, 0x100
	s_addc_u32 s13, s13, 0
	s_add_u32 s37, s37, 0x100
	s_addc_u32 s60, s60, 0
	s_cmp_gt_u32 s61, 29
	s_cbranch_scc0 .LBB0_187
	s_and_b64 vcc, exec, s[96:97]
	s_cbranch_vccz .LBB0_190
	s_barrier

; #define PG8_STAGE(bufoff, gbase, voff) do { _Pragma("unroll") for (int _i = 0; _i < 2; ++_i) \
;         __builtin_amdgcn_global_load_lds((const unsigned*)((const char*)(gbase) + (voff)[_i]), (PG8_LAS unsigned*)(lds + (bufoff) + ldsw + _i * 8192), 16, 0, 0); } while (0)
; #define PG8_LDA(dst, b, h) do { _Pragma("unroll") for (int m = 0; m < 4; ++m) _Pragma("unroll") for (int k = 0; k < 2; ++k) dst[m][k] = *(const PG8_LAS bf16x8*)(lds + PG8_SA(b, h) + aoff + m * 2048 + k * 1024); } while (0)
; #define PG8_LDB(dst, b, h) do { _Pragma("unroll") for (int n = 0; n < 2; ++n) _Pragma("unroll") for (int k = 0; k < 2; ++k) dst[n][k] = *(const PG8_LAS bf16x8*)(lds + PG8_SB(b, h) + boff + n * 2048 + k * 1024); } while (0)
; #define PG8_MMA(ai, bj, At, Bt) do { __builtin_amdgcn_s_setprio(1); _Pragma("unroll") for (int m = 0; m < 4; ++m) _Pragma("unroll") for (int n = 0; n < 2; ++n) _Pragma("unroll") for (int k = 0; k < 2; ++k) \
;         acc[ai][bj][m][n] = __builtin_amdgcn_mfma_f32_16x16x32_bf16(Bt[n][k], At[m][k], acc[ai][bj][m][n], 0, 0, 0); __builtin_amdgcn_s_setprio(0); } while (0)
; #define PG8_WAIT_V(n) asm volatile("s_waitcnt vmcnt(" #n ")" ::: "memory")
; template <class Epi, class Sched, bool ALIGN_EPI = false, bool SP2 = false>
; __device__ __forceinline__ void gemm_phase(PG8_LAS unsigned char* lds, const Gemm g, const Sched& S, const Epi& E) {
;     ...
;             const bool last = (t == nt - 2);
;             if constexpr (Epi::HAS_MID) { if (t == E.mid_t) E.mid(acc, cur, wr, wc, fr, fq); }
;             const char* a1 = cA + (size_t)(t + 1) * kstep;
;             const char* a2 = last ? nA : cA + (size_t)(t + 2) * kstep; const char* b2 = last ? nB : cB + (size_t)(t + 2) * kstep;
;             const char* a3 = a2 + kstep; const char* b3 = b2 + kstep;
;             if (last && has_next) S.a_ready(nxt);
;             if constexpr (SP2) {
;             PG8_LDB(B0, 0, 0); PG8_LDB(B1, 0, 1); PG8_SCHED; PG8_LDA(At, 0, 0); PG8_STAGE(PG8_SA(1, 1), a1 + hstepA, voffA);
;             PG8_WAIT_V(8); PG8_WAIT_L(0); PG8_BAR; PG8_MMA(0, 0, At, B0); PG8_MMA(0, 1, At, B1); PG8_BAR; PG8_SCHED;
;             PG8_LDA(At, 0, 1); PG8_STAGE(PG8_SB(0, 0), b2, voffB); PG8_STAGE(PG8_SB(0, 1), b2 + hstepB, voffB); PG8_STAGE(PG8_SA(0, 0), a2, voffA);
;             PG8_WAIT_V(8); PG8_WAIT_L(0); PG8_BAR; PG8_MMA(1, 0, At, B0); PG8_MMA(1, 1, At, B1); PG8_BAR; PG8_SCHED;
.LBB0_1217:
	v_add_u32_e32 v1, s57, v154
	ds_read_b128 v[158:161], v1
	ds_read_b128 v[162:165], v1 offset:1024
	ds_read_b128 v[166:169], v1 offset:2048
	ds_read_b128 v[170:173], v1 offset:3072
	v_add_u32_e32 v1, s58, v154
	s_add_u32 s42, s78, s18
	ds_read_b128 v[174:177], v1
	ds_read_b128 v[178:181], v1 offset:1024
	ds_read_b128 v[182:185], v1 offset:2048
	ds_read_b128 v[186:189], v1 offset:3072
	s_addc_u32 s43, s79, s19
	s_add_u32 s42, s42, 0x100
	s_addc_u32 s43, s43, 0
	s_add_u32 s69, s66, s18
	s_addc_u32 s70, s67, s19
	s_cmpk_eq_i32 s18, 0xf00
	s_cselect_b32 s43, s62, s43
	s_cselect_b32 s42, s63, s42
	s_cselect_b32 vcc_hi, s51, s70
	s_cselect_b32 vcc_lo, s65, s69
	v_lshl_add_u64 v[2:3], v[148:149], 0, s[18:19]
	s_add_i32 m0, s5, 0xc000
	ds_read_b128 v[190:193], v156
	ds_read_b128 v[194:197], v156 offset:1024
	ds_read_b128 v[198:201], v156 offset:2048
	ds_read_b128 v[202:205], v156 offset:3072
	ds_read_b128 v[206:209], v156 offset:4096
	ds_read_b128 v[210:213], v156 offset:5120
	ds_read_b128 v[214:217], v156 offset:6144
	ds_read_b128 v[218:221], v156 offset:7168
	s_add_u32 s98, s78, s18
	s_addc_u32 s99, s79, s19
	s_add_u32 s98, s98, 0x80
	s_addc_u32 s99, s99, 0
	s_mov_b32 m0, s47
	s_nop 0
	global_load_lds_dwordx4 v132, s[98:99]
	s_mov_b32 m0, s56
	s_nop 0
	global_load_lds_dwordx4 v136, s[98:99]
	s_add_i32 m0, s5, 0xc000
	s_nop 0
	global_load_lds_dwordx4 v[2:3], off
	v_lshl_add_u64 v[2:3], v[150:151], 0, s[18:19]
	s_add_i32 m0, s5, 0xe000
	s_nop 0
	global_load_lds_dwordx4 v[2:3], off
	s_waitcnt vmcnt(8)
	s_waitcnt lgkmcnt(0)
	s_barrier
	s_setprio 1
	v_mfma_f32_16x16x32_bf16 v[128:131], v[158:161], v[190:193], v[128:131]
	v_mfma_f32_16x16x32_bf16 v[124:127], v[166:169], v[190:193], v[124:127]
	v_mfma_f32_16x16x32_bf16 v[112:115], v[158:161], v[198:201], v[112:115]
	v_mfma_f32_16x16x32_bf16 v[108:111], v[166:169], v[198:201], v[108:111]
	v_mfma_f32_16x16x32_bf16 v[96:99], v[158:161], v[206:209], v[96:99]
	v_mfma_f32_16x16x32_bf16 v[92:95], v[166:169], v[206:209], v[92:95]
	v_mfma_f32_16x16x32_bf16 v[80:83], v[158:161], v[214:217], v[80:83]
	v_mfma_f32_16x16x32_bf16 v[76:79], v[166:169], v[214:217], v[76:79]
	v_mfma_f32_16x16x32_bf16 v[128:131], v[162:165], v[194:197], v[128:131]
	v_mfma_f32_16x16x32_bf16 v[124:127], v[170:173], v[194:197], v[124:127]
	v_mfma_f32_16x16x32_bf16 v[112:115], v[162:165], v[202:205], v[112:115]
	v_mfma_f32_16x16x32_bf16 v[108:111], v[170:173], v[202:205], v[108:111]
	v_mfma_f32_16x16x32_bf16 v[96:99], v[162:165], v[210:213], v[96:99]
	v_mfma_f32_16x16x32_bf16 v[92:95], v[170:173], v[210:213], v[92:95]
	v_mfma_f32_16x16x32_bf16 v[80:83], v[162:165], v[218:221], v[80:83]
	v_mfma_f32_16x16x32_bf16 v[76:79], v[170:173], v[218:221], v[76:79]
	s_setprio 0
	s_setprio 1
	v_mfma_f32_16x16x32_bf16 v[120:123], v[174:177], v[190:193], v[120:123]
	v_mfma_f32_16x16x32_bf16 v[116:119], v[182:185], v[190:193], v[116:119]
	v_mfma_f32_16x16x32_bf16 v[104:107], v[174:177], v[198:201], v[104:107]
	v_mfma_f32_16x16x32_bf16 v[100:103], v[182:185], v[198:201], v[100:103]
	v_mfma_f32_16x16x32_bf16 v[88:91], v[174:177], v[206:209], v[88:91]
	v_mfma_f32_16x16x32_bf16 v[84:87], v[182:185], v[206:209], v[84:87]
	v_mfma_f32_16x16x32_bf16 v[72:75], v[174:177], v[214:217], v[72:75]
	v_mfma_f32_16x16x32_bf16 v[68:71], v[182:185], v[214:217], v[68:71]
	v_mfma_f32_16x16x32_bf16 v[120:123], v[178:181], v[194:197], v[120:123]
	v_mfma_f32_16x16x32_bf16 v[116:119], v[186:189], v[194:197], v[116:119]
	v_mfma_f32_16x16x32_bf16 v[104:107], v[178:181], v[202:205], v[104:107]
	v_mfma_f32_16x16x32_bf16 v[100:103], v[186:189], v[202:205], v[100:103]
	v_mfma_f32_16x16x32_bf16 v[88:91], v[178:181], v[210:213], v[88:91]
	v_mfma_f32_16x16x32_bf16 v[84:87], v[186:189], v[210:213], v[84:87]
	v_mfma_f32_16x16x32_bf16 v[72:75], v[178:181], v[218:221], v[72:75]
	v_mfma_f32_16x16x32_bf16 v[68:71], v[186:189], v[218:221], v[68:71]
	s_setprio 0
	s_barrier
	s_add_i32 s69, s57, s4
	s_mov_b32 m0, s69
	ds_read_b128 v[190:193], v156 offset:16384
	ds_read_b128 v[194:197], v156 offset:17408
	ds_read_b128 v[198:201], v156 offset:18432
	ds_read_b128 v[202:205], v156 offset:19456
	ds_read_b128 v[206:209], v156 offset:20480
	ds_read_b128 v[210:213], v156 offset:21504
	ds_read_b128 v[214:217], v156 offset:22528
	ds_read_b128 v[218:221], v156 offset:23552
	global_load_lds_dwordx4 v134, vcc
	s_add_i32 m0, s69, 0x2000
	s_add_u32 s70, vcc_lo, 0x80000
	s_addc_u32 s71, vcc_hi, 0
	s_add_i32 s69, s58, s4
	global_load_lds_dwordx4 v138, vcc
	s_mov_b32 m0, s69
	s_nop 0
	global_load_lds_dwordx4 v134, s[70:71]
	s_add_i32 m0, s69, 0x2000
	s_nop 0
	global_load_lds_dwordx4 v138, s[70:71]
	s_waitcnt vmcnt(6)
	s_waitcnt lgkmcnt(0)
	s_barrier
; #define PG8_STAGE(bufoff, gbase, voff) do { _Pragma("unroll") for (int _i = 0; _i < 2; ++_i) \
;         __builtin_amdgcn_global_load_lds((const unsigned*)((const char*)(gbase) + (voff)[_i]), (PG8_LAS unsigned*)(lds + (bufoff) + ldsw + _i * 8192), 16, 0, 0); } while (0)
; #define PG8_LDA(dst, b, h) do { _Pragma("unroll") for (int m = 0; m < 4; ++m) _Pragma("unroll") for (int k = 0; k < 2; ++k) dst[m][k] = *(const PG8_LAS bf16x8*)(lds + PG8_SA(b, h) + aoff + m * 2048 + k * 1024); } while (0)
; #define PG8_LDB(dst, b, h) do { _Pragma("unroll") for (int n = 0; n < 2; ++n) _Pragma("unroll") for (int k = 0; k < 2; ++k) dst[n][k] = *(const PG8_LAS bf16x8*)(lds + PG8_SB(b, h) + boff + n * 2048 + k * 1024); } while (0)
; #define PG8_MMA(ai, bj, At, Bt) do { __builtin_amdgcn_s_setprio(1); _Pragma("unroll") for (int m = 0; m < 4; ++m) _Pragma("unroll") for (int n = 0; n < 2; ++n) _Pragma("unroll") for (int k = 0; k < 2; ++k) \
;         acc[ai][bj][m][n] = __builtin_amdgcn_mfma_f32_16x16x32_bf16(Bt[n][k], At[m][k], acc[ai][bj][m][n], 0, 0, 0); __builtin_amdgcn_s_setprio(0); } while (0)
; #define PG8_WAIT_V(n) asm volatile("s_waitcnt vmcnt(" #n ")" ::: "memory")
; #define PG8_WAIT_L(n) asm volatile("s_waitcnt lgkmcnt(" #n ")" ::: "memory")
; #define PG8_BAR __builtin_amdgcn_s_barrier()
; #define PG8_SCHED __builtin_amdgcn_sched_barrier(0)
; template <class Epi, class Sched, bool ALIGN_EPI = false, bool SP2 = false>
; __device__ __forceinline__ void gemm_phase(PG8_LAS unsigned char* lds, const Gemm g, const Sched& S, const Epi& E) {
;     ...
;             PG8_WAIT_V(8); PG8_WAIT_L(0); PG8_BAR; PG8_MMA(1, 0, At, B0); PG8_MMA(1, 1, At, B1); PG8_BAR; PG8_SCHED;
;             PG8_LDB(B0, 1, 0); PG8_LDB(B1, 1, 1); PG8_SCHED; PG8_LDA(At, 1, 0); PG8_STAGE(PG8_SA(0, 1), a2 + hstepA, voffA);
;             PG8_WAIT_V(8); PG8_WAIT_L(0); PG8_BAR; PG8_MMA(0, 0, At, B0); PG8_MMA(0, 1, At, B1); PG8_BAR; PG8_SCHED;
	s_setprio 1
	v_mfma_f32_16x16x32_bf16 v[64:67], v[158:161], v[190:193], v[64:67]
	v_mfma_f32_16x16x32_bf16 v[60:63], v[166:169], v[190:193], v[60:63]
	v_mfma_f32_16x16x32_bf16 v[48:51], v[158:161], v[198:201], v[48:51]
	v_mfma_f32_16x16x32_bf16 v[44:47], v[166:169], v[198:201], v[44:47]
	v_mfma_f32_16x16x32_bf16 v[32:35], v[158:161], v[206:209], v[32:35]
	v_mfma_f32_16x16x32_bf16 v[28:31], v[166:169], v[206:209], v[28:31]
	v_mfma_f32_16x16x32_bf16 v[16:19], v[158:161], v[214:217], v[16:19]
	v_mfma_f32_16x16x32_bf16 v[12:15], v[166:169], v[214:217], v[12:15]
	v_mfma_f32_16x16x32_bf16 v[64:67], v[162:165], v[194:197], v[64:67]
	v_mfma_f32_16x16x32_bf16 v[60:63], v[170:173], v[194:197], v[60:63]
	v_mfma_f32_16x16x32_bf16 v[48:51], v[162:165], v[202:205], v[48:51]
	v_mfma_f32_16x16x32_bf16 v[44:47], v[170:173], v[202:205], v[44:47]
	v_mfma_f32_16x16x32_bf16 v[32:35], v[162:165], v[210:213], v[32:35]
	v_mfma_f32_16x16x32_bf16 v[28:31], v[170:173], v[210:213], v[28:31]
	v_mfma_f32_16x16x32_bf16 v[16:19], v[162:165], v[218:221], v[16:19]
	v_mfma_f32_16x16x32_bf16 v[12:15], v[170:173], v[218:221], v[12:15]
	s_setprio 0
	s_setprio 1
	v_mfma_f32_16x16x32_bf16 v[56:59], v[174:177], v[190:193], v[56:59]
	v_mfma_f32_16x16x32_bf16 v[52:55], v[182:185], v[190:193], v[52:55]
	v_mfma_f32_16x16x32_bf16 v[40:43], v[174:177], v[198:201], v[40:43]
	v_mfma_f32_16x16x32_bf16 v[36:39], v[182:185], v[198:201], v[36:39]
	v_mfma_f32_16x16x32_bf16 v[24:27], v[174:177], v[206:209], v[24:27]
	v_mfma_f32_16x16x32_bf16 v[20:23], v[182:185], v[206:209], v[20:23]
	v_mfma_f32_16x16x32_bf16 v[8:11], v[174:177], v[214:217], v[8:11]
	v_mfma_f32_16x16x32_bf16 v[2:5], v[182:185], v[214:217], v[4:7]
	v_mfma_f32_16x16x32_bf16 v[56:59], v[178:181], v[194:197], v[56:59]
	v_mfma_f32_16x16x32_bf16 v[52:55], v[186:189], v[194:197], v[52:55]
	v_mfma_f32_16x16x32_bf16 v[40:43], v[178:181], v[202:205], v[40:43]
	v_mfma_f32_16x16x32_bf16 v[36:39], v[186:189], v[202:205], v[36:39]
	v_mfma_f32_16x16x32_bf16 v[24:27], v[178:181], v[210:213], v[24:27]
	v_mfma_f32_16x16x32_bf16 v[20:23], v[186:189], v[210:213], v[20:23]
	v_mfma_f32_16x16x32_bf16 v[8:11], v[178:181], v[218:221], v[8:11]
	v_mfma_f32_16x16x32_bf16 v[2:5], v[186:189], v[218:221], v[2:5]
	s_setprio 0
	s_barrier
	s_add_i32 s69, 0, 0x18000
	v_add_u32_e32 v1, s69, v154
	s_add_i32 s70, 0, 0x1c000
	ds_read_b128 v[158:161], v1
	ds_read_b128 v[162:165], v1 offset:1024
	ds_read_b128 v[166:169], v1 offset:2048
	ds_read_b128 v[170:173], v1 offset:3072
	v_add_u32_e32 v1, s70, v154
	ds_read_b128 v[174:177], v1
	ds_read_b128 v[178:181], v1 offset:1024
	ds_read_b128 v[182:185], v1 offset:2048
	ds_read_b128 v[186:189], v1 offset:3072
	s_mov_b64 s[100:101], s[42:43]
	s_add_u32 s42, s42, 0x80000
	s_addc_u32 s43, s43, 0
	s_mov_b32 m0, s7
	ds_read_b128 v[190:193], v156 offset:32768
	ds_read_b128 v[194:197], v156 offset:33792
	ds_read_b128 v[198:201], v156 offset:34816
	ds_read_b128 v[202:205], v156 offset:35840
	ds_read_b128 v[206:209], v156 offset:36864
	ds_read_b128 v[210:213], v156 offset:37888
	ds_read_b128 v[214:217], v156 offset:38912
	ds_read_b128 v[218:221], v156 offset:39936
	s_mov_b32 m0, s5
	s_nop 0
	global_load_lds_dwordx4 v132, s[100:101]
	s_mov_b32 m0, s6
	s_nop 0
	global_load_lds_dwordx4 v136, s[100:101]
	s_mov_b32 m0, s7
	s_nop 0
	global_load_lds_dwordx4 v132, s[42:43]
	s_mov_b32 m0, s33
	s_nop 0
	global_load_lds_dwordx4 v136, s[42:43]
	s_waitcnt vmcnt(8)
	s_waitcnt lgkmcnt(0)
	s_barrier
; #define PG8_STAGE(bufoff, gbase, voff) do { _Pragma("unroll") for (int _i = 0; _i < 2; ++_i) \
;         __builtin_amdgcn_global_load_lds((const unsigned*)((const char*)(gbase) + (voff)[_i]), (PG8_LAS unsigned*)(lds + (bufoff) + ldsw + _i * 8192), 16, 0, 0); } while (0)
; #define PG8_LDA(dst, b, h) do { _Pragma("unroll") for (int m = 0; m < 4; ++m) _Pragma("unroll") for (int k = 0; k < 2; ++k) dst[m][k] = *(const PG8_LAS bf16x8*)(lds + PG8_SA(b, h) + aoff + m * 2048 + k * 1024); } while (0)
; #define PG8_MMA(ai, bj, At, Bt) do { __builtin_amdgcn_s_setprio(1); _Pragma("unroll") for (int m = 0; m < 4; ++m) _Pragma("unroll") for (int n = 0; n < 2; ++n) _Pragma("unroll") for (int k = 0; k < 2; ++k) \
;         acc[ai][bj][m][n] = __builtin_amdgcn_mfma_f32_16x16x32_bf16(Bt[n][k], At[m][k], acc[ai][bj][m][n], 0, 0, 0); __builtin_amdgcn_s_setprio(0); } while (0)
; #define PG8_WAIT_V(n) asm volatile("s_waitcnt vmcnt(" #n ")" ::: "memory")
; #define PG8_WAIT_L(n) asm volatile("s_waitcnt lgkmcnt(" #n ")" ::: "memory")
; #define PG8_BAR __builtin_amdgcn_s_barrier()
; #define PG8_SCHED __builtin_amdgcn_sched_barrier(0)
; template <class Epi, class Sched, bool ALIGN_EPI = false, bool SP2 = false>
; __device__ __forceinline__ void gemm_phase(PG8_LAS unsigned char* lds, const Gemm g, const Sched& S, const Epi& E) {
;     ...
;             PG8_WAIT_V(8); PG8_WAIT_L(0); PG8_BAR; PG8_MMA(0, 0, At, B0); PG8_MMA(0, 1, At, B1); PG8_BAR; PG8_SCHED;
;             PG8_LDA(At, 1, 1); PG8_STAGE(PG8_SB(1, 0), b3, voffB); PG8_STAGE(PG8_SB(1, 1), b3 + hstepB, voffB); PG8_STAGE(PG8_SA(1, 0), a3, voffA);
;             PG8_WAIT_V(8); PG8_WAIT_L(0); PG8_BAR; PG8_MMA(1, 0, At, B0); PG8_MMA(1, 1, At, B1); PG8_BAR; PG8_SCHED;
	s_setprio 1
	v_mfma_f32_16x16x32_bf16 v[128:131], v[158:161], v[190:193], v[128:131]
	v_mfma_f32_16x16x32_bf16 v[124:127], v[166:169], v[190:193], v[124:127]
	v_mfma_f32_16x16x32_bf16 v[112:115], v[158:161], v[198:201], v[112:115]
	v_mfma_f32_16x16x32_bf16 v[108:111], v[166:169], v[198:201], v[108:111]
	v_mfma_f32_16x16x32_bf16 v[96:99], v[158:161], v[206:209], v[96:99]
	v_mfma_f32_16x16x32_bf16 v[92:95], v[166:169], v[206:209], v[92:95]
	v_mfma_f32_16x16x32_bf16 v[80:83], v[158:161], v[214:217], v[80:83]
	v_mfma_f32_16x16x32_bf16 v[76:79], v[166:169], v[214:217], v[76:79]
	v_mfma_f32_16x16x32_bf16 v[128:131], v[162:165], v[194:197], v[128:131]
	v_mfma_f32_16x16x32_bf16 v[124:127], v[170:173], v[194:197], v[124:127]
	v_mfma_f32_16x16x32_bf16 v[112:115], v[162:165], v[202:205], v[112:115]
	v_mfma_f32_16x16x32_bf16 v[108:111], v[170:173], v[202:205], v[108:111]
	v_mfma_f32_16x16x32_bf16 v[96:99], v[162:165], v[210:213], v[96:99]
	v_mfma_f32_16x16x32_bf16 v[92:95], v[170:173], v[210:213], v[92:95]
	v_mfma_f32_16x16x32_bf16 v[80:83], v[162:165], v[218:221], v[80:83]
	v_mfma_f32_16x16x32_bf16 v[76:79], v[170:173], v[218:221], v[76:79]
	s_setprio 0
	s_setprio 1
	v_mfma_f32_16x16x32_bf16 v[120:123], v[174:177], v[190:193], v[120:123]
	v_mfma_f32_16x16x32_bf16 v[116:119], v[182:185], v[190:193], v[116:119]
	v_mfma_f32_16x16x32_bf16 v[104:107], v[174:177], v[198:201], v[104:107]
	v_mfma_f32_16x16x32_bf16 v[100:103], v[182:185], v[198:201], v[100:103]
	v_mfma_f32_16x16x32_bf16 v[88:91], v[174:177], v[206:209], v[88:91]
	v_mfma_f32_16x16x32_bf16 v[84:87], v[182:185], v[206:209], v[84:87]
	v_mfma_f32_16x16x32_bf16 v[72:75], v[174:177], v[214:217], v[72:75]
	v_mfma_f32_16x16x32_bf16 v[68:71], v[182:185], v[214:217], v[68:71]
	v_mfma_f32_16x16x32_bf16 v[120:123], v[178:181], v[194:197], v[120:123]
	v_mfma_f32_16x16x32_bf16 v[116:119], v[186:189], v[194:197], v[116:119]
	v_mfma_f32_16x16x32_bf16 v[104:107], v[178:181], v[202:205], v[104:107]
	v_mfma_f32_16x16x32_bf16 v[100:103], v[186:189], v[202:205], v[100:103]
	v_mfma_f32_16x16x32_bf16 v[88:91], v[178:181], v[210:213], v[88:91]
	v_mfma_f32_16x16x32_bf16 v[84:87], v[186:189], v[210:213], v[84:87]
	v_mfma_f32_16x16x32_bf16 v[72:75], v[178:181], v[218:221], v[72:75]
	v_mfma_f32_16x16x32_bf16 v[68:71], v[186:189], v[218:221], v[68:71]
	s_setprio 0
	s_barrier
	s_add_i32 s42, s69, s4
	s_add_u32 s98, vcc_lo, 0x80
	s_addc_u32 s99, vcc_hi, 0
	s_mov_b32 m0, s42
	ds_read_b128 v[190:193], v156 offset:49152
	ds_read_b128 v[194:197], v156 offset:50176
	ds_read_b128 v[198:201], v156 offset:51200
	ds_read_b128 v[202:205], v156 offset:52224
	ds_read_b128 v[206:209], v156 offset:53248
	ds_read_b128 v[210:213], v156 offset:54272
	ds_read_b128 v[214:217], v156 offset:55296
	ds_read_b128 v[218:221], v156 offset:56320
	global_load_lds_dwordx4 v134, s[98:99]
	s_add_i32 m0, s42, 0x2000
	s_add_u32 s42, vcc_lo, 0x80080
	s_addc_u32 s43, vcc_hi, 0
	s_add_i32 s69, s70, s4
	global_load_lds_dwordx4 v138, s[98:99]
	s_mov_b32 m0, s69
	s_nop 0
	global_load_lds_dwordx4 v134, s[42:43]
	s_add_i32 m0, s69, 0x2000
	s_nop 0
	global_load_lds_dwordx4 v138, s[42:43]
	s_waitcnt vmcnt(6)
	s_waitcnt lgkmcnt(0)
	s_barrier
	s_setprio 1
	v_mfma_f32_16x16x32_bf16 v[64:67], v[158:161], v[190:193], v[64:67]
	v_mfma_f32_16x16x32_bf16 v[60:63], v[166:169], v[190:193], v[60:63]
	v_mfma_f32_16x16x32_bf16 v[48:51], v[158:161], v[198:201], v[48:51]
	v_mfma_f32_16x16x32_bf16 v[44:47], v[166:169], v[198:201], v[44:47]
	v_mfma_f32_16x16x32_bf16 v[32:35], v[158:161], v[206:209], v[32:35]
	v_mfma_f32_16x16x32_bf16 v[28:31], v[166:169], v[206:209], v[28:31]
	v_mfma_f32_16x16x32_bf16 v[16:19], v[158:161], v[214:217], v[16:19]
	v_mfma_f32_16x16x32_bf16 v[12:15], v[166:169], v[214:217], v[12:15]
	v_mfma_f32_16x16x32_bf16 v[64:67], v[162:165], v[194:197], v[64:67]
	v_mfma_f32_16x16x32_bf16 v[60:63], v[170:173], v[194:197], v[60:63]
	v_mfma_f32_16x16x32_bf16 v[48:51], v[162:165], v[202:205], v[48:51]
	v_mfma_f32_16x16x32_bf16 v[44:47], v[170:173], v[202:205], v[44:47]
	v_mfma_f32_16x16x32_bf16 v[32:35], v[162:165], v[210:213], v[32:35]
	v_mfma_f32_16x16x32_bf16 v[28:31], v[170:173], v[210:213], v[28:31]
	v_mfma_f32_16x16x32_bf16 v[16:19], v[162:165], v[218:221], v[16:19]
	v_mfma_f32_16x16x32_bf16 v[12:15], v[170:173], v[218:221], v[12:15]
	s_setprio 0
	s_setprio 1
	v_mfma_f32_16x16x32_bf16 v[56:59], v[174:177], v[190:193], v[56:59]
	v_mfma_f32_16x16x32_bf16 v[52:55], v[182:185], v[190:193], v[52:55]
	v_mfma_f32_16x16x32_bf16 v[40:43], v[174:177], v[198:201], v[40:43]
	v_mfma_f32_16x16x32_bf16 v[36:39], v[182:185], v[198:201], v[36:39]
	v_mfma_f32_16x16x32_bf16 v[24:27], v[174:177], v[206:209], v[24:27]
	v_mfma_f32_16x16x32_bf16 v[20:23], v[182:185], v[206:209], v[20:23]
	v_mfma_f32_16x16x32_bf16 v[6:9], v[174:177], v[214:217], v[8:11]
	v_mfma_f32_16x16x32_bf16 v[2:5], v[182:185], v[214:217], v[2:5]
	v_mfma_f32_16x16x32_bf16 v[56:59], v[178:181], v[194:197], v[56:59]
	v_mfma_f32_16x16x32_bf16 v[52:55], v[186:189], v[194:197], v[52:55]
	v_mfma_f32_16x16x32_bf16 v[40:43], v[178:181], v[202:205], v[40:43]
	v_mfma_f32_16x16x32_bf16 v[36:39], v[186:189], v[202:205], v[36:39]
	v_mfma_f32_16x16x32_bf16 v[24:27], v[178:181], v[210:213], v[24:27]
	v_mfma_f32_16x16x32_bf16 v[20:23], v[186:189], v[210:213], v[20:23]
	v_mfma_f32_16x16x32_bf16 v[8:11], v[178:181], v[218:221], v[6:9]
	v_mfma_f32_16x16x32_bf16 v[4:7], v[186:189], v[218:221], v[2:5]
	s_setprio 0
	s_barrier
	s_add_i32 s68, s68, 2
	s_add_u32 s18, s18, 0x100
	s_addc_u32 s19, s19, 0
	s_cmp_gt_u32 s68, 29
	s_cbranch_scc1 .LBB0_1220

; #define PG8_STAGE(bufoff, gbase, voff) do { _Pragma("unroll") for (int _i = 0; _i < 2; ++_i) \
;         __builtin_amdgcn_global_load_lds((const unsigned*)((const char*)(gbase) + (voff)[_i]), (PG8_LAS unsigned*)(lds + (bufoff) + ldsw + _i * 8192), 16, 0, 0); } while (0)
; #define PG8_LDA(dst, b, h) do { _Pragma("unroll") for (int m = 0; m < 4; ++m) _Pragma("unroll") for (int k = 0; k < 2; ++k) dst[m][k] = *(const PG8_LAS bf16x8*)(lds + PG8_SA(b, h) + aoff + m * 2048 + k * 1024); } while (0)
; #define PG8_LDB(dst, b, h) do { _Pragma("unroll") for (int n = 0; n < 2; ++n) _Pragma("unroll") for (int k = 0; k < 2; ++k) dst[n][k] = *(const PG8_LAS bf16x8*)(lds + PG8_SB(b, h) + boff + n * 2048 + k * 1024); } while (0)
; #define PG8_MMA(ai, bj, At, Bt) do { __builtin_amdgcn_s_setprio(1); _Pragma("unroll") for (int m = 0; m < 4; ++m) _Pragma("unroll") for (int n = 0; n < 2; ++n) _Pragma("unroll") for (int k = 0; k < 2; ++k) \
;         acc[ai][bj][m][n] = __builtin_amdgcn_mfma_f32_16x16x32_bf16(Bt[n][k], At[m][k], acc[ai][bj][m][n], 0, 0, 0); __builtin_amdgcn_s_setprio(0); } while (0)
; #define PG8_WAIT_V(n) asm volatile("s_waitcnt vmcnt(" #n ")" ::: "memory")
; template <class Epi, class Sched, bool ALIGN_EPI = false, bool SP2 = false>
; __device__ __forceinline__ void gemm_phase(PG8_LAS unsigned char* lds, const Gemm g, const Sched& S, const Epi& E) {
;     ...
;             const bool last = (t == nt - 2);
;             if constexpr (Epi::HAS_MID) { if (t == E.mid_t) E.mid(acc, cur, wr, wc, fr, fq); }
;             const char* a1 = cA + (size_t)(t + 1) * kstep;
;             const char* a2 = last ? nA : cA + (size_t)(t + 2) * kstep; const char* b2 = last ? nB : cB + (size_t)(t + 2) * kstep;
;             const char* a3 = a2 + kstep; const char* b3 = b2 + kstep;
;             if (last && has_next) S.a_ready(nxt);
;             if constexpr (SP2) {
;             PG8_LDB(B0, 0, 0); PG8_LDB(B1, 0, 1); PG8_SCHED; PG8_LDA(At, 0, 0); PG8_STAGE(PG8_SA(1, 1), a1 + hstepA, voffA);
;             PG8_WAIT_V(8); PG8_WAIT_L(0); PG8_BAR; PG8_MMA(0, 0, At, B0); PG8_MMA(0, 1, At, B1); PG8_BAR; PG8_SCHED;
;             PG8_LDA(At, 0, 1); PG8_STAGE(PG8_SB(0, 0), b2, voffB); PG8_STAGE(PG8_SB(0, 1), b2 + hstepB, voffB); PG8_STAGE(PG8_SA(0, 0), a2, voffA);
;             PG8_WAIT_V(8); PG8_WAIT_L(0); PG8_BAR; PG8_MMA(1, 0, At, B0); PG8_MMA(1, 1, At, B1); PG8_BAR; PG8_SCHED;
.LBB0_1309:
	ds_read_b128 v[128:131], v161
	ds_read_b128 v[132:135], v161 offset:1024
	ds_read_b128 v[148:151], v161 offset:2048
	ds_read_b128 v[152:155], v161 offset:3072
	ds_read_b128 v[166:169], v162
	ds_read_b128 v[170:173], v162 offset:1024
	ds_read_b128 v[174:177], v162 offset:2048
	ds_read_b128 v[178:181], v162 offset:3072
	s_add_u32 s16, s12, 0xfff80080
	s_addc_u32 s17, s13, -1
	s_cmp_eq_u32 s65, 28
	s_cselect_b32 s19, s39, s17
	s_cselect_b32 s18, s59, s16
	s_cselect_b32 s17, s37, s63
	s_cselect_b32 s16, s61, s62
	s_add_i32 m0, s5, 0xc000
	ds_read_b128 v[182:185], v163
	ds_read_b128 v[186:189], v163 offset:1024
	ds_read_b128 v[190:193], v163 offset:2048
	ds_read_b128 v[194:197], v163 offset:3072
	ds_read_b128 v[198:201], v163 offset:4096
	ds_read_b128 v[202:205], v163 offset:5120
	ds_read_b128 v[206:209], v163 offset:6144
	ds_read_b128 v[210:213], v163 offset:7168
	s_add_u32 s98, s12, 0xfff80000
	s_addc_u32 s99, s13, -1
	s_mov_b32 m0, s33
	s_nop 0
	global_load_lds_dwordx4 v136, s[98:99]
	s_mov_b32 m0, s34
	s_nop 0
	global_load_lds_dwordx4 v140, s[98:99]
	s_add_i32 m0, s5, 0xc000
	s_nop 0
	global_load_lds_dwordx4 v144, s[12:13]
	s_add_i32 m0, s5, 0xe000
	s_nop 0
	global_load_lds_dwordx4 v146, s[12:13]
	s_waitcnt vmcnt(8)
	s_waitcnt lgkmcnt(0)
	s_barrier
	s_setprio 1
	v_mfma_f32_16x16x32_bf16 v[124:127], v[128:131], v[182:185], v[124:127]
	v_mfma_f32_16x16x32_bf16 v[120:123], v[148:151], v[182:185], v[120:123]
	v_mfma_f32_16x16x32_bf16 v[108:111], v[128:131], v[190:193], v[108:111]
	v_mfma_f32_16x16x32_bf16 v[104:107], v[148:151], v[190:193], v[104:107]
	v_mfma_f32_16x16x32_bf16 v[92:95], v[128:131], v[198:201], v[92:95]
	v_mfma_f32_16x16x32_bf16 v[88:91], v[148:151], v[198:201], v[88:91]
	v_mfma_f32_16x16x32_bf16 v[76:79], v[128:131], v[206:209], v[76:79]
	v_mfma_f32_16x16x32_bf16 v[72:75], v[148:151], v[206:209], v[72:75]
	v_mfma_f32_16x16x32_bf16 v[124:127], v[132:135], v[186:189], v[124:127]
	v_mfma_f32_16x16x32_bf16 v[120:123], v[152:155], v[186:189], v[120:123]
	v_mfma_f32_16x16x32_bf16 v[108:111], v[132:135], v[194:197], v[108:111]
	v_mfma_f32_16x16x32_bf16 v[104:107], v[152:155], v[194:197], v[104:107]
	v_mfma_f32_16x16x32_bf16 v[92:95], v[132:135], v[202:205], v[92:95]
	v_mfma_f32_16x16x32_bf16 v[88:91], v[152:155], v[202:205], v[88:91]
	v_mfma_f32_16x16x32_bf16 v[76:79], v[132:135], v[210:213], v[76:79]
	v_mfma_f32_16x16x32_bf16 v[72:75], v[152:155], v[210:213], v[72:75]
	s_setprio 0
	s_setprio 1
	v_mfma_f32_16x16x32_bf16 v[116:119], v[166:169], v[182:185], v[116:119]
	v_mfma_f32_16x16x32_bf16 v[112:115], v[174:177], v[182:185], v[112:115]
	v_mfma_f32_16x16x32_bf16 v[100:103], v[166:169], v[190:193], v[100:103]
	v_mfma_f32_16x16x32_bf16 v[96:99], v[174:177], v[190:193], v[96:99]
	v_mfma_f32_16x16x32_bf16 v[84:87], v[166:169], v[198:201], v[84:87]
	v_mfma_f32_16x16x32_bf16 v[80:83], v[174:177], v[198:201], v[80:83]
	v_mfma_f32_16x16x32_bf16 v[68:71], v[166:169], v[206:209], v[68:71]
	v_mfma_f32_16x16x32_bf16 v[64:67], v[174:177], v[206:209], v[64:67]
	v_mfma_f32_16x16x32_bf16 v[116:119], v[170:173], v[186:189], v[116:119]
	v_mfma_f32_16x16x32_bf16 v[112:115], v[178:181], v[186:189], v[112:115]
	v_mfma_f32_16x16x32_bf16 v[100:103], v[170:173], v[194:197], v[100:103]
	v_mfma_f32_16x16x32_bf16 v[96:99], v[178:181], v[194:197], v[96:99]
	v_mfma_f32_16x16x32_bf16 v[84:87], v[170:173], v[202:205], v[84:87]
	v_mfma_f32_16x16x32_bf16 v[80:83], v[178:181], v[202:205], v[80:83]
	v_mfma_f32_16x16x32_bf16 v[68:71], v[170:173], v[210:213], v[68:71]
	v_mfma_f32_16x16x32_bf16 v[64:67], v[178:181], v[210:213], v[64:67]
	s_setprio 0
	s_barrier
	s_add_i32 s66, s56, s4
	s_mov_b32 m0, s66
	ds_read_b128 v[182:185], v163 offset:16384
	ds_read_b128 v[186:189], v163 offset:17408
	ds_read_b128 v[190:193], v163 offset:18432
	ds_read_b128 v[194:197], v163 offset:19456
	ds_read_b128 v[198:201], v163 offset:20480
	ds_read_b128 v[202:205], v163 offset:21504
	ds_read_b128 v[206:209], v163 offset:22528
	ds_read_b128 v[210:213], v163 offset:23552
	global_load_lds_dwordx4 v138, s[16:17]
	s_add_i32 m0, s66, 0x2000
	s_add_u32 s66, s16, 0x80000
	s_addc_u32 s67, s17, 0
	s_add_i32 s68, s57, s4
	global_load_lds_dwordx4 v142, s[16:17]
	s_mov_b32 m0, s68
	s_nop 0
	global_load_lds_dwordx4 v138, s[66:67]
	s_add_i32 m0, s68, 0x2000
	s_nop 0
	global_load_lds_dwordx4 v142, s[66:67]
	s_waitcnt vmcnt(6)
	s_waitcnt lgkmcnt(0)
	s_barrier
	s_setprio 1
	v_mfma_f32_16x16x32_bf16 v[60:63], v[128:131], v[182:185], v[60:63]
	v_mfma_f32_16x16x32_bf16 v[56:59], v[148:151], v[182:185], v[56:59]
	v_mfma_f32_16x16x32_bf16 v[44:47], v[128:131], v[190:193], v[44:47]
	v_mfma_f32_16x16x32_bf16 v[40:43], v[148:151], v[190:193], v[40:43]
	v_mfma_f32_16x16x32_bf16 v[28:31], v[128:131], v[198:201], v[28:31]
	v_mfma_f32_16x16x32_bf16 v[24:27], v[148:151], v[198:201], v[24:27]
	v_mfma_f32_16x16x32_bf16 v[12:15], v[128:131], v[206:209], v[12:15]
	v_mfma_f32_16x16x32_bf16 v[8:11], v[148:151], v[206:209], v[8:11]
	v_mfma_f32_16x16x32_bf16 v[60:63], v[132:135], v[186:189], v[60:63]
	v_mfma_f32_16x16x32_bf16 v[56:59], v[152:155], v[186:189], v[56:59]
	v_mfma_f32_16x16x32_bf16 v[44:47], v[132:135], v[194:197], v[44:47]
	v_mfma_f32_16x16x32_bf16 v[40:43], v[152:155], v[194:197], v[40:43]
	v_mfma_f32_16x16x32_bf16 v[28:31], v[132:135], v[202:205], v[28:31]
	v_mfma_f32_16x16x32_bf16 v[24:27], v[152:155], v[202:205], v[24:27]
	v_mfma_f32_16x16x32_bf16 v[12:15], v[132:135], v[210:213], v[12:15]
	v_mfma_f32_16x16x32_bf16 v[8:11], v[152:155], v[210:213], v[8:11]
	s_setprio 0
	s_setprio 1
	v_mfma_f32_16x16x32_bf16 v[52:55], v[166:169], v[182:185], v[52:55]
	v_mfma_f32_16x16x32_bf16 v[48:51], v[174:177], v[182:185], v[48:51]
	v_mfma_f32_16x16x32_bf16 v[36:39], v[166:169], v[190:193], v[36:39]
	v_mfma_f32_16x16x32_bf16 v[32:35], v[174:177], v[190:193], v[32:35]
	v_mfma_f32_16x16x32_bf16 v[20:23], v[166:169], v[198:201], v[20:23]
	v_mfma_f32_16x16x32_bf16 v[16:19], v[174:177], v[198:201], v[16:19]
	v_mfma_f32_16x16x32_bf16 v[4:7], v[166:169], v[206:209], v[4:7]
	v_mfma_f32_16x16x32_bf16 v[0:3], v[174:177], v[206:209], v[0:3]
	v_mfma_f32_16x16x32_bf16 v[52:55], v[170:173], v[186:189], v[52:55]
	v_mfma_f32_16x16x32_bf16 v[48:51], v[178:181], v[186:189], v[48:51]
	v_mfma_f32_16x16x32_bf16 v[36:39], v[170:173], v[194:197], v[36:39]
	v_mfma_f32_16x16x32_bf16 v[32:35], v[178:181], v[194:197], v[32:35]
	v_mfma_f32_16x16x32_bf16 v[20:23], v[170:173], v[202:205], v[20:23]
	v_mfma_f32_16x16x32_bf16 v[16:19], v[178:181], v[202:205], v[16:19]
	v_mfma_f32_16x16x32_bf16 v[4:7], v[170:173], v[210:213], v[4:7]
	v_mfma_f32_16x16x32_bf16 v[0:3], v[178:181], v[210:213], v[0:3]
	s_setprio 0
	s_barrier
; #define PG8_STAGE(bufoff, gbase, voff) do { _Pragma("unroll") for (int _i = 0; _i < 2; ++_i) \
;         __builtin_amdgcn_global_load_lds((const unsigned*)((const char*)(gbase) + (voff)[_i]), (PG8_LAS unsigned*)(lds + (bufoff) + ldsw + _i * 8192), 16, 0, 0); } while (0)
; #define PG8_LDA(dst, b, h) do { _Pragma("unroll") for (int m = 0; m < 4; ++m) _Pragma("unroll") for (int k = 0; k < 2; ++k) dst[m][k] = *(const PG8_LAS bf16x8*)(lds + PG8_SA(b, h) + aoff + m * 2048 + k * 1024); } while (0)
; #define PG8_LDB(dst, b, h) do { _Pragma("unroll") for (int n = 0; n < 2; ++n) _Pragma("unroll") for (int k = 0; k < 2; ++k) dst[n][k] = *(const PG8_LAS bf16x8*)(lds + PG8_SB(b, h) + boff + n * 2048 + k * 1024); } while (0)
; #define PG8_MMA(ai, bj, At, Bt) do { __builtin_amdgcn_s_setprio(1); _Pragma("unroll") for (int m = 0; m < 4; ++m) _Pragma("unroll") for (int n = 0; n < 2; ++n) _Pragma("unroll") for (int k = 0; k < 2; ++k) \
;         acc[ai][bj][m][n] = __builtin_amdgcn_mfma_f32_16x16x32_bf16(Bt[n][k], At[m][k], acc[ai][bj][m][n], 0, 0, 0); __builtin_amdgcn_s_setprio(0); } while (0)
; #define PG8_WAIT_V(n) asm volatile("s_waitcnt vmcnt(" #n ")" ::: "memory")
; #define PG8_WAIT_L(n) asm volatile("s_waitcnt lgkmcnt(" #n ")" ::: "memory")
; #define PG8_BAR __builtin_amdgcn_s_barrier()
; #define PG8_SCHED __builtin_amdgcn_sched_barrier(0)
; template <class Epi, class Sched, bool ALIGN_EPI = false, bool SP2 = false>
; __device__ __forceinline__ void gemm_phase(PG8_LAS unsigned char* lds, const Gemm g, const Sched& S, const Epi& E) {
;     ...
;             PG8_LDB(B0, 1, 0); PG8_LDB(B1, 1, 1); PG8_SCHED; PG8_LDA(At, 1, 0); PG8_STAGE(PG8_SA(0, 1), a2 + hstepA, voffA);
;             PG8_WAIT_V(8); PG8_WAIT_L(0); PG8_BAR; PG8_MMA(0, 0, At, B0); PG8_MMA(0, 1, At, B1); PG8_BAR; PG8_SCHED;
;             PG8_LDA(At, 1, 1); PG8_STAGE(PG8_SB(1, 0), b3, voffB); PG8_STAGE(PG8_SB(1, 1), b3 + hstepB, voffB); PG8_STAGE(PG8_SA(1, 0), a3, voffA);
;             PG8_WAIT_V(8); PG8_WAIT_L(0); PG8_BAR; PG8_MMA(1, 0, At, B0); PG8_MMA(1, 1, At, B1); PG8_BAR; PG8_SCHED;
;     ...
;         if constexpr (ALIGN_EPI) { if (wr == 0) PG8_BAR; }
	s_add_i32 s66, 0, 0x18000
	s_add_i32 s67, 0, 0x1c000
	v_add_u32_e32 v152, s66, v160
	v_add_u32_e32 v165, s67, v160
	ds_read_b128 v[128:131], v152
	ds_read_b128 v[132:135], v152 offset:1024
	ds_read_b128 v[148:151], v152 offset:2048
	ds_read_b128 v[152:155], v152 offset:3072
	ds_read_b128 v[166:169], v165
	ds_read_b128 v[170:173], v165 offset:1024
	ds_read_b128 v[174:177], v165 offset:2048
	ds_read_b128 v[178:181], v165 offset:3072
	s_mov_b64 s[100:101], s[18:19]
	s_add_u32 s18, s18, 0x80000
	s_addc_u32 s19, s19, 0
	s_mov_b32 m0, s7
	ds_read_b128 v[182:185], v163 offset:32768
	ds_read_b128 v[186:189], v163 offset:33792
	ds_read_b128 v[190:193], v163 offset:34816
	ds_read_b128 v[194:197], v163 offset:35840
	ds_read_b128 v[198:201], v163 offset:36864
	ds_read_b128 v[202:205], v163 offset:37888
	ds_read_b128 v[206:209], v163 offset:38912
	ds_read_b128 v[210:213], v163 offset:39936
	s_mov_b32 m0, s5
	s_nop 0
	global_load_lds_dwordx4 v136, s[100:101]
	s_mov_b32 m0, s6
	s_nop 0
	global_load_lds_dwordx4 v140, s[100:101]
	s_mov_b32 m0, s7
	s_nop 0
	global_load_lds_dwordx4 v136, s[18:19]
	s_mov_b32 m0, s20
	s_nop 0
	global_load_lds_dwordx4 v140, s[18:19]
	s_waitcnt vmcnt(8)
	s_waitcnt lgkmcnt(0)
	s_barrier
	s_setprio 1
	v_mfma_f32_16x16x32_bf16 v[124:127], v[128:131], v[182:185], v[124:127]
	v_mfma_f32_16x16x32_bf16 v[120:123], v[148:151], v[182:185], v[120:123]
	v_mfma_f32_16x16x32_bf16 v[108:111], v[128:131], v[190:193], v[108:111]
	v_mfma_f32_16x16x32_bf16 v[104:107], v[148:151], v[190:193], v[104:107]
	v_mfma_f32_16x16x32_bf16 v[92:95], v[128:131], v[198:201], v[92:95]
	v_mfma_f32_16x16x32_bf16 v[88:91], v[148:151], v[198:201], v[88:91]
	v_mfma_f32_16x16x32_bf16 v[76:79], v[128:131], v[206:209], v[76:79]
	v_mfma_f32_16x16x32_bf16 v[72:75], v[148:151], v[206:209], v[72:75]
	v_mfma_f32_16x16x32_bf16 v[124:127], v[132:135], v[186:189], v[124:127]
	v_mfma_f32_16x16x32_bf16 v[120:123], v[152:155], v[186:189], v[120:123]
	v_mfma_f32_16x16x32_bf16 v[108:111], v[132:135], v[194:197], v[108:111]
	v_mfma_f32_16x16x32_bf16 v[104:107], v[152:155], v[194:197], v[104:107]
	v_mfma_f32_16x16x32_bf16 v[92:95], v[132:135], v[202:205], v[92:95]
	v_mfma_f32_16x16x32_bf16 v[88:91], v[152:155], v[202:205], v[88:91]
	v_mfma_f32_16x16x32_bf16 v[76:79], v[132:135], v[210:213], v[76:79]
	v_mfma_f32_16x16x32_bf16 v[72:75], v[152:155], v[210:213], v[72:75]
	s_setprio 0
	s_setprio 1
	v_mfma_f32_16x16x32_bf16 v[116:119], v[166:169], v[182:185], v[116:119]
	v_mfma_f32_16x16x32_bf16 v[112:115], v[174:177], v[182:185], v[112:115]
	v_mfma_f32_16x16x32_bf16 v[100:103], v[166:169], v[190:193], v[100:103]
	v_mfma_f32_16x16x32_bf16 v[96:99], v[174:177], v[190:193], v[96:99]
	v_mfma_f32_16x16x32_bf16 v[84:87], v[166:169], v[198:201], v[84:87]
	v_mfma_f32_16x16x32_bf16 v[80:83], v[174:177], v[198:201], v[80:83]
	v_mfma_f32_16x16x32_bf16 v[68:71], v[166:169], v[206:209], v[68:71]
	v_mfma_f32_16x16x32_bf16 v[64:67], v[174:177], v[206:209], v[64:67]
	v_mfma_f32_16x16x32_bf16 v[116:119], v[170:173], v[186:189], v[116:119]
	v_mfma_f32_16x16x32_bf16 v[112:115], v[178:181], v[186:189], v[112:115]
	v_mfma_f32_16x16x32_bf16 v[100:103], v[170:173], v[194:197], v[100:103]
	v_mfma_f32_16x16x32_bf16 v[96:99], v[178:181], v[194:197], v[96:99]
	v_mfma_f32_16x16x32_bf16 v[84:87], v[170:173], v[202:205], v[84:87]
	v_mfma_f32_16x16x32_bf16 v[80:83], v[178:181], v[202:205], v[80:83]
	v_mfma_f32_16x16x32_bf16 v[68:71], v[170:173], v[210:213], v[68:71]
	v_mfma_f32_16x16x32_bf16 v[64:67], v[178:181], v[210:213], v[64:67]
	s_setprio 0
	s_barrier
	s_add_i32 s18, s66, s4
	s_add_u32 s98, s16, 0x80
	s_addc_u32 s99, s17, 0
	s_mov_b32 m0, s18
	ds_read_b128 v[182:185], v163 offset:49152
	ds_read_b128 v[186:189], v163 offset:50176
	ds_read_b128 v[190:193], v163 offset:51200
	ds_read_b128 v[194:197], v163 offset:52224
	ds_read_b128 v[198:201], v163 offset:53248
	ds_read_b128 v[202:205], v163 offset:54272
	ds_read_b128 v[206:209], v163 offset:55296
	ds_read_b128 v[210:213], v163 offset:56320
	global_load_lds_dwordx4 v138, s[98:99]
	s_add_i32 m0, s18, 0x2000
	s_add_u32 s16, s16, 0x80080
	s_addc_u32 s17, s17, 0
	s_add_i32 s18, s67, s4
	global_load_lds_dwordx4 v142, s[98:99]
	s_mov_b32 m0, s18
	s_nop 0
	global_load_lds_dwordx4 v138, s[16:17]
	s_add_i32 m0, s18, 0x2000
	s_nop 0
	global_load_lds_dwordx4 v142, s[16:17]
	s_waitcnt vmcnt(6)
	s_waitcnt lgkmcnt(0)
	s_barrier
	s_setprio 1
	v_mfma_f32_16x16x32_bf16 v[60:63], v[128:131], v[182:185], v[60:63]
	v_mfma_f32_16x16x32_bf16 v[56:59], v[148:151], v[182:185], v[56:59]
	v_mfma_f32_16x16x32_bf16 v[44:47], v[128:131], v[190:193], v[44:47]
	v_mfma_f32_16x16x32_bf16 v[40:43], v[148:151], v[190:193], v[40:43]
	v_mfma_f32_16x16x32_bf16 v[28:31], v[128:131], v[198:201], v[28:31]
	v_mfma_f32_16x16x32_bf16 v[24:27], v[148:151], v[198:201], v[24:27]
	v_mfma_f32_16x16x32_bf16 v[12:15], v[128:131], v[206:209], v[12:15]
	v_mfma_f32_16x16x32_bf16 v[8:11], v[148:151], v[206:209], v[8:11]
	v_mfma_f32_16x16x32_bf16 v[60:63], v[132:135], v[186:189], v[60:63]
	v_mfma_f32_16x16x32_bf16 v[56:59], v[152:155], v[186:189], v[56:59]
	v_mfma_f32_16x16x32_bf16 v[44:47], v[132:135], v[194:197], v[44:47]
	v_mfma_f32_16x16x32_bf16 v[40:43], v[152:155], v[194:197], v[40:43]
	v_mfma_f32_16x16x32_bf16 v[28:31], v[132:135], v[202:205], v[28:31]
	v_mfma_f32_16x16x32_bf16 v[24:27], v[152:155], v[202:205], v[24:27]
	v_mfma_f32_16x16x32_bf16 v[12:15], v[132:135], v[210:213], v[12:15]
	v_mfma_f32_16x16x32_bf16 v[8:11], v[152:155], v[210:213], v[8:11]
	s_setprio 0
	s_setprio 1
	v_mfma_f32_16x16x32_bf16 v[52:55], v[166:169], v[182:185], v[52:55]
	v_mfma_f32_16x16x32_bf16 v[48:51], v[174:177], v[182:185], v[48:51]
	v_mfma_f32_16x16x32_bf16 v[36:39], v[166:169], v[190:193], v[36:39]
	v_mfma_f32_16x16x32_bf16 v[32:35], v[174:177], v[190:193], v[32:35]
	v_mfma_f32_16x16x32_bf16 v[20:23], v[166:169], v[198:201], v[20:23]
	v_mfma_f32_16x16x32_bf16 v[16:19], v[174:177], v[198:201], v[16:19]
	v_mfma_f32_16x16x32_bf16 v[4:7], v[166:169], v[206:209], v[4:7]
	v_mfma_f32_16x16x32_bf16 v[0:3], v[174:177], v[206:209], v[0:3]
	v_mfma_f32_16x16x32_bf16 v[52:55], v[170:173], v[186:189], v[52:55]
	v_mfma_f32_16x16x32_bf16 v[48:51], v[178:181], v[186:189], v[48:51]
	v_mfma_f32_16x16x32_bf16 v[36:39], v[170:173], v[194:197], v[36:39]
	v_mfma_f32_16x16x32_bf16 v[32:35], v[178:181], v[194:197], v[32:35]
	v_mfma_f32_16x16x32_bf16 v[20:23], v[170:173], v[202:205], v[20:23]
	v_mfma_f32_16x16x32_bf16 v[16:19], v[178:181], v[202:205], v[16:19]
	v_mfma_f32_16x16x32_bf16 v[4:7], v[170:173], v[210:213], v[4:7]
	v_mfma_f32_16x16x32_bf16 v[0:3], v[178:181], v[210:213], v[0:3]
	s_setprio 0
	s_barrier
	s_add_i32 s65, s65, 2
	s_add_u32 s12, s12, 0x100
	s_addc_u32 s13, s13, 0
	s_add_u32 s62, s62, 0x100
	s_addc_u32 s63, s63, 0
	s_cmp_gt_u32 s65, 29
	s_cbranch_scc0 .LBB0_1309
	s_and_b64 vcc, exec, s[26:27]
	s_cbranch_vccz .LBB0_1312
	s_barrier

; #define PG8_STAGE(bufoff, gbase, voff) do { _Pragma("unroll") for (int _i = 0; _i < 2; ++_i) \
;         __builtin_amdgcn_global_load_lds((const unsigned*)((const char*)(gbase) + (voff)[_i]), (PG8_LAS unsigned*)(lds + (bufoff) + ldsw + _i * 8192), 16, 0, 0); } while (0)
; #define PG8_LDA(dst, b, h) do { _Pragma("unroll") for (int m = 0; m < 4; ++m) _Pragma("unroll") for (int k = 0; k < 2; ++k) dst[m][k] = *(const PG8_LAS bf16x8*)(lds + PG8_SA(b, h) + aoff + m * 2048 + k * 1024); } while (0)
; #define PG8_LDB(dst, b, h) do { _Pragma("unroll") for (int n = 0; n < 2; ++n) _Pragma("unroll") for (int k = 0; k < 2; ++k) dst[n][k] = *(const PG8_LAS bf16x8*)(lds + PG8_SB(b, h) + boff + n * 2048 + k * 1024); } while (0)
; #define PG8_MMA(ai, bj, At, Bt) do { __builtin_amdgcn_s_setprio(1); _Pragma("unroll") for (int m = 0; m < 4; ++m) _Pragma("unroll") for (int n = 0; n < 2; ++n) _Pragma("unroll") for (int k = 0; k < 2; ++k) \
;         acc[ai][bj][m][n] = __builtin_amdgcn_mfma_f32_16x16x32_bf16(Bt[n][k], At[m][k], acc[ai][bj][m][n], 0, 0, 0); __builtin_amdgcn_s_setprio(0); } while (0)
; #define PG8_WAIT_V(n) asm volatile("s_waitcnt vmcnt(" #n ")" ::: "memory")
; template <class Epi, class Sched, bool ALIGN_EPI = false, bool SP2 = false>
; __device__ __forceinline__ void gemm_phase(PG8_LAS unsigned char* lds, const Gemm g, const Sched& S, const Epi& E) {
;     ...
;             const bool last = (t == nt - 2);
;             if constexpr (Epi::HAS_MID) { if (t == E.mid_t) E.mid(acc, cur, wr, wc, fr, fq); }
;             const char* a1 = cA + (size_t)(t + 1) * kstep;
;             const char* a2 = last ? nA : cA + (size_t)(t + 2) * kstep; const char* b2 = last ? nB : cB + (size_t)(t + 2) * kstep;
;             const char* a3 = a2 + kstep; const char* b3 = b2 + kstep;
;             if (last && has_next) S.a_ready(nxt);
;             if constexpr (SP2) {
;             PG8_LDB(B0, 0, 0); PG8_LDB(B1, 0, 1); PG8_SCHED; PG8_LDA(At, 0, 0); PG8_STAGE(PG8_SA(1, 1), a1 + hstepA, voffA);
;             PG8_WAIT_V(8); PG8_WAIT_L(0); PG8_BAR; PG8_MMA(0, 0, At, B0); PG8_MMA(0, 1, At, B1); PG8_BAR; PG8_SCHED;
;             PG8_LDA(At, 0, 1); PG8_STAGE(PG8_SB(0, 0), b2, voffB); PG8_STAGE(PG8_SB(0, 1), b2 + hstepB, voffB); PG8_STAGE(PG8_SA(0, 0), a2, voffA);
;             PG8_WAIT_V(8); PG8_WAIT_L(0); PG8_BAR; PG8_MMA(1, 0, At, B0); PG8_MMA(1, 1, At, B1); PG8_BAR; PG8_SCHED;
.LBB0_1363:
	ds_read_b128 v[128:131], v169
	ds_read_b128 v[132:135], v169 offset:1024
	ds_read_b128 v[148:151], v169 offset:2048
	ds_read_b128 v[152:155], v169 offset:3072
	ds_read_b128 v[156:159], v170
	ds_read_b128 v[160:163], v170 offset:1024
	ds_read_b128 v[174:177], v170 offset:2048
	ds_read_b128 v[178:181], v170 offset:3072
	s_add_u32 s20, s16, 0xfff80080
	s_addc_u32 s21, s17, -1
	s_cmp_eq_u32 s63, 28
	s_cselect_b32 s35, s13, s21
	s_cselect_b32 s34, s19, s20
	s_cselect_b32 s21, s29, s62
	s_cselect_b32 s20, s31, s61
	v_lshl_add_u64 v[164:165], s[16:17], 0, v[144:145]
	s_add_i32 m0, s6, 0xc000
	ds_read_b128 v[182:185], v171
	ds_read_b128 v[186:189], v171 offset:1024
	ds_read_b128 v[190:193], v171 offset:2048
	ds_read_b128 v[194:197], v171 offset:3072
	ds_read_b128 v[198:201], v171 offset:4096
	ds_read_b128 v[202:205], v171 offset:5120
	ds_read_b128 v[206:209], v171 offset:6144
	ds_read_b128 v[210:213], v171 offset:7168
	global_load_lds_dwordx4 v[164:165], off
	v_lshl_add_u64 v[164:165], s[16:17], 0, v[146:147]
	s_add_i32 m0, s6, 0xe000
	s_nop 0
	global_load_lds_dwordx4 v[164:165], off
	s_waitcnt vmcnt(8)
	s_waitcnt lgkmcnt(0)
	s_barrier
	s_setprio 1
	v_mfma_f32_16x16x32_bf16 v[124:127], v[128:131], v[182:185], v[124:127]
	v_mfma_f32_16x16x32_bf16 v[120:123], v[148:151], v[182:185], v[120:123]
	v_mfma_f32_16x16x32_bf16 v[108:111], v[128:131], v[190:193], v[108:111]
	v_mfma_f32_16x16x32_bf16 v[104:107], v[148:151], v[190:193], v[104:107]
	v_mfma_f32_16x16x32_bf16 v[92:95], v[128:131], v[198:201], v[92:95]
	v_mfma_f32_16x16x32_bf16 v[88:91], v[148:151], v[198:201], v[88:91]
	v_mfma_f32_16x16x32_bf16 v[76:79], v[128:131], v[206:209], v[76:79]
	v_mfma_f32_16x16x32_bf16 v[72:75], v[148:151], v[206:209], v[72:75]
	v_mfma_f32_16x16x32_bf16 v[124:127], v[132:135], v[186:189], v[124:127]
	v_mfma_f32_16x16x32_bf16 v[120:123], v[152:155], v[186:189], v[120:123]
	v_mfma_f32_16x16x32_bf16 v[108:111], v[132:135], v[194:197], v[108:111]
	v_mfma_f32_16x16x32_bf16 v[104:107], v[152:155], v[194:197], v[104:107]
	v_mfma_f32_16x16x32_bf16 v[92:95], v[132:135], v[202:205], v[92:95]
	v_mfma_f32_16x16x32_bf16 v[88:91], v[152:155], v[202:205], v[88:91]
	v_mfma_f32_16x16x32_bf16 v[76:79], v[132:135], v[210:213], v[76:79]
	v_mfma_f32_16x16x32_bf16 v[72:75], v[152:155], v[210:213], v[72:75]
	s_setprio 0
	s_setprio 1
	v_mfma_f32_16x16x32_bf16 v[116:119], v[156:159], v[182:185], v[116:119]
	v_mfma_f32_16x16x32_bf16 v[112:115], v[174:177], v[182:185], v[112:115]
	v_mfma_f32_16x16x32_bf16 v[100:103], v[156:159], v[190:193], v[100:103]
	v_mfma_f32_16x16x32_bf16 v[96:99], v[174:177], v[190:193], v[96:99]
	v_mfma_f32_16x16x32_bf16 v[84:87], v[156:159], v[198:201], v[84:87]
	v_mfma_f32_16x16x32_bf16 v[80:83], v[174:177], v[198:201], v[80:83]
	v_mfma_f32_16x16x32_bf16 v[68:71], v[156:159], v[206:209], v[68:71]
	v_mfma_f32_16x16x32_bf16 v[64:67], v[174:177], v[206:209], v[64:67]
	v_mfma_f32_16x16x32_bf16 v[116:119], v[160:163], v[186:189], v[116:119]
	v_mfma_f32_16x16x32_bf16 v[112:115], v[178:181], v[186:189], v[112:115]
	v_mfma_f32_16x16x32_bf16 v[100:103], v[160:163], v[194:197], v[100:103]
	v_mfma_f32_16x16x32_bf16 v[96:99], v[178:181], v[194:197], v[96:99]
	v_mfma_f32_16x16x32_bf16 v[84:87], v[160:163], v[202:205], v[84:87]
	v_mfma_f32_16x16x32_bf16 v[80:83], v[178:181], v[202:205], v[80:83]
	v_mfma_f32_16x16x32_bf16 v[68:71], v[160:163], v[210:213], v[68:71]
	v_mfma_f32_16x16x32_bf16 v[64:67], v[178:181], v[210:213], v[64:67]
	s_setprio 0
	s_barrier
	s_add_i32 s64, s59, s5
	v_lshl_add_u64 v[164:165], s[20:21], 0, v[138:139]
	s_mov_b32 m0, s64
	ds_read_b128 v[182:185], v171 offset:16384
	ds_read_b128 v[186:189], v171 offset:17408
	ds_read_b128 v[190:193], v171 offset:18432
	ds_read_b128 v[194:197], v171 offset:19456
	ds_read_b128 v[198:201], v171 offset:20480
	ds_read_b128 v[202:205], v171 offset:21504
	ds_read_b128 v[206:209], v171 offset:22528
	ds_read_b128 v[210:213], v171 offset:23552
	global_load_lds_dwordx4 v[164:165], off
	s_add_i32 m0, s64, 0x2000
	s_add_u32 s64, s20, 0x80000
	v_lshl_add_u64 v[214:215], s[20:21], 0, v[142:143]
	s_addc_u32 s65, s21, 0
	s_add_i32 s66, s60, s5
	global_load_lds_dwordx4 v[214:215], off
	v_lshl_add_u64 v[216:217], s[64:65], 0, v[138:139]
	s_mov_b32 m0, s66
	v_lshl_add_u64 v[218:219], s[34:35], 0, v[140:141]
	global_load_lds_dwordx4 v[216:217], off
	v_lshl_add_u64 v[216:217], s[64:65], 0, v[142:143]
	s_add_i32 m0, s66, 0x2000
	s_nop 0
	global_load_lds_dwordx4 v[216:217], off
	v_lshl_add_u64 v[216:217], s[34:35], 0, v[136:137]
	s_mov_b32 m0, s6
	s_nop 0
	global_load_lds_dwordx4 v[216:217], off
	s_mov_b32 m0, s7
	s_nop 0
	global_load_lds_dwordx4 v[218:219], off
	s_waitcnt vmcnt(8)
	s_waitcnt lgkmcnt(0)
	s_barrier
; #define PG8_STAGE(bufoff, gbase, voff) do { _Pragma("unroll") for (int _i = 0; _i < 2; ++_i) \
;         __builtin_amdgcn_global_load_lds((const unsigned*)((const char*)(gbase) + (voff)[_i]), (PG8_LAS unsigned*)(lds + (bufoff) + ldsw + _i * 8192), 16, 0, 0); } while (0)
; #define PG8_LDA(dst, b, h) do { _Pragma("unroll") for (int m = 0; m < 4; ++m) _Pragma("unroll") for (int k = 0; k < 2; ++k) dst[m][k] = *(const PG8_LAS bf16x8*)(lds + PG8_SA(b, h) + aoff + m * 2048 + k * 1024); } while (0)
; #define PG8_LDB(dst, b, h) do { _Pragma("unroll") for (int n = 0; n < 2; ++n) _Pragma("unroll") for (int k = 0; k < 2; ++k) dst[n][k] = *(const PG8_LAS bf16x8*)(lds + PG8_SB(b, h) + boff + n * 2048 + k * 1024); } while (0)
; #define PG8_MMA(ai, bj, At, Bt) do { __builtin_amdgcn_s_setprio(1); _Pragma("unroll") for (int m = 0; m < 4; ++m) _Pragma("unroll") for (int n = 0; n < 2; ++n) _Pragma("unroll") for (int k = 0; k < 2; ++k) \
;         acc[ai][bj][m][n] = __builtin_amdgcn_mfma_f32_16x16x32_bf16(Bt[n][k], At[m][k], acc[ai][bj][m][n], 0, 0, 0); __builtin_amdgcn_s_setprio(0); } while (0)
; #define PG8_WAIT_V(n) asm volatile("s_waitcnt vmcnt(" #n ")" ::: "memory")
; #define PG8_WAIT_L(n) asm volatile("s_waitcnt lgkmcnt(" #n ")" ::: "memory")
; #define PG8_BAR __builtin_amdgcn_s_barrier()
; #define PG8_SCHED __builtin_amdgcn_sched_barrier(0)
; template <class Epi, class Sched, bool ALIGN_EPI = false, bool SP2 = false>
; __device__ __forceinline__ void gemm_phase(PG8_LAS unsigned char* lds, const Gemm g, const Sched& S, const Epi& E) {
;     ...
;             PG8_WAIT_V(8); PG8_WAIT_L(0); PG8_BAR; PG8_MMA(1, 0, At, B0); PG8_MMA(1, 1, At, B1); PG8_BAR; PG8_SCHED;
;             PG8_LDB(B0, 1, 0); PG8_LDB(B1, 1, 1); PG8_SCHED; PG8_LDA(At, 1, 0); PG8_STAGE(PG8_SA(0, 1), a2 + hstepA, voffA);
;             PG8_WAIT_V(8); PG8_WAIT_L(0); PG8_BAR; PG8_MMA(0, 0, At, B0); PG8_MMA(0, 1, At, B1); PG8_BAR; PG8_SCHED;
	s_setprio 1
	v_mfma_f32_16x16x32_bf16 v[60:63], v[128:131], v[182:185], v[60:63]
	v_mfma_f32_16x16x32_bf16 v[56:59], v[148:151], v[182:185], v[56:59]
	v_mfma_f32_16x16x32_bf16 v[44:47], v[128:131], v[190:193], v[44:47]
	v_mfma_f32_16x16x32_bf16 v[40:43], v[148:151], v[190:193], v[40:43]
	v_mfma_f32_16x16x32_bf16 v[28:31], v[128:131], v[198:201], v[28:31]
	v_mfma_f32_16x16x32_bf16 v[24:27], v[148:151], v[198:201], v[24:27]
	v_mfma_f32_16x16x32_bf16 v[12:15], v[128:131], v[206:209], v[12:15]
	v_mfma_f32_16x16x32_bf16 v[8:11], v[148:151], v[206:209], v[8:11]
	v_mfma_f32_16x16x32_bf16 v[60:63], v[132:135], v[186:189], v[60:63]
	v_mfma_f32_16x16x32_bf16 v[56:59], v[152:155], v[186:189], v[56:59]
	v_mfma_f32_16x16x32_bf16 v[44:47], v[132:135], v[194:197], v[44:47]
	v_mfma_f32_16x16x32_bf16 v[40:43], v[152:155], v[194:197], v[40:43]
	v_mfma_f32_16x16x32_bf16 v[28:31], v[132:135], v[202:205], v[28:31]
	v_mfma_f32_16x16x32_bf16 v[24:27], v[152:155], v[202:205], v[24:27]
	v_mfma_f32_16x16x32_bf16 v[12:15], v[132:135], v[210:213], v[12:15]
	v_mfma_f32_16x16x32_bf16 v[8:11], v[152:155], v[210:213], v[8:11]
	s_setprio 0
	s_setprio 1
	v_mfma_f32_16x16x32_bf16 v[52:55], v[156:159], v[182:185], v[52:55]
	v_mfma_f32_16x16x32_bf16 v[48:51], v[174:177], v[182:185], v[48:51]
	v_mfma_f32_16x16x32_bf16 v[36:39], v[156:159], v[190:193], v[36:39]
	v_mfma_f32_16x16x32_bf16 v[32:35], v[174:177], v[190:193], v[32:35]
	v_mfma_f32_16x16x32_bf16 v[20:23], v[156:159], v[198:201], v[20:23]
	v_mfma_f32_16x16x32_bf16 v[16:19], v[174:177], v[198:201], v[16:19]
	v_mfma_f32_16x16x32_bf16 v[4:7], v[156:159], v[206:209], v[4:7]
	v_mfma_f32_16x16x32_bf16 v[0:3], v[174:177], v[206:209], v[0:3]
	v_mfma_f32_16x16x32_bf16 v[52:55], v[160:163], v[186:189], v[52:55]
	v_mfma_f32_16x16x32_bf16 v[48:51], v[178:181], v[186:189], v[48:51]
	v_mfma_f32_16x16x32_bf16 v[36:39], v[160:163], v[194:197], v[36:39]
	v_mfma_f32_16x16x32_bf16 v[32:35], v[178:181], v[194:197], v[32:35]
	v_mfma_f32_16x16x32_bf16 v[20:23], v[160:163], v[202:205], v[20:23]
	v_mfma_f32_16x16x32_bf16 v[16:19], v[178:181], v[202:205], v[16:19]
	v_mfma_f32_16x16x32_bf16 v[4:7], v[160:163], v[210:213], v[4:7]
	v_mfma_f32_16x16x32_bf16 v[0:3], v[178:181], v[210:213], v[0:3]
	s_setprio 0
	s_barrier
	s_add_i32 s64, 0, 0x18000
	s_add_i32 s65, 0, 0x1c000
	v_add_u32_e32 v152, s64, v168
	v_add_u32_e32 v173, s65, v168
	ds_read_b128 v[128:131], v152
	ds_read_b128 v[132:135], v152 offset:1024
	ds_read_b128 v[148:151], v152 offset:2048
	ds_read_b128 v[152:155], v152 offset:3072
	ds_read_b128 v[156:159], v173
	ds_read_b128 v[160:163], v173 offset:1024
	ds_read_b128 v[174:177], v173 offset:2048
	ds_read_b128 v[178:181], v173 offset:3072
	s_add_u32 s34, s34, 0x80000
	s_addc_u32 s35, s35, 0
	s_mov_b32 m0, s33
	v_lshl_add_u64 v[220:221], s[34:35], 0, v[136:137]
	ds_read_b128 v[182:185], v171 offset:32768
	ds_read_b128 v[186:189], v171 offset:33792
	ds_read_b128 v[190:193], v171 offset:34816
	ds_read_b128 v[194:197], v171 offset:35840
	ds_read_b128 v[198:201], v171 offset:36864
	ds_read_b128 v[202:205], v171 offset:37888
	ds_read_b128 v[206:209], v171 offset:38912
	ds_read_b128 v[210:213], v171 offset:39936
	global_load_lds_dwordx4 v[220:221], off
	v_lshl_add_u64 v[220:221], s[34:35], 0, v[140:141]
	s_mov_b32 m0, s46
	s_nop 0
	global_load_lds_dwordx4 v[220:221], off
	s_waitcnt vmcnt(8)
	s_waitcnt lgkmcnt(0)
	s_barrier
	s_setprio 1
	v_mfma_f32_16x16x32_bf16 v[124:127], v[128:131], v[182:185], v[124:127]
	v_mfma_f32_16x16x32_bf16 v[120:123], v[148:151], v[182:185], v[120:123]
	v_mfma_f32_16x16x32_bf16 v[108:111], v[128:131], v[190:193], v[108:111]
	v_mfma_f32_16x16x32_bf16 v[104:107], v[148:151], v[190:193], v[104:107]
	v_mfma_f32_16x16x32_bf16 v[92:95], v[128:131], v[198:201], v[92:95]
	v_mfma_f32_16x16x32_bf16 v[88:91], v[148:151], v[198:201], v[88:91]
	v_mfma_f32_16x16x32_bf16 v[76:79], v[128:131], v[206:209], v[76:79]
	v_mfma_f32_16x16x32_bf16 v[72:75], v[148:151], v[206:209], v[72:75]
	v_mfma_f32_16x16x32_bf16 v[124:127], v[132:135], v[186:189], v[124:127]
	v_mfma_f32_16x16x32_bf16 v[120:123], v[152:155], v[186:189], v[120:123]
	v_mfma_f32_16x16x32_bf16 v[108:111], v[132:135], v[194:197], v[108:111]
	v_mfma_f32_16x16x32_bf16 v[104:107], v[152:155], v[194:197], v[104:107]
	v_mfma_f32_16x16x32_bf16 v[92:95], v[132:135], v[202:205], v[92:95]
	v_mfma_f32_16x16x32_bf16 v[88:91], v[152:155], v[202:205], v[88:91]
	v_mfma_f32_16x16x32_bf16 v[76:79], v[132:135], v[210:213], v[76:79]
	v_mfma_f32_16x16x32_bf16 v[72:75], v[152:155], v[210:213], v[72:75]
	s_setprio 0
	s_setprio 1
	v_mfma_f32_16x16x32_bf16 v[116:119], v[156:159], v[182:185], v[116:119]
	v_mfma_f32_16x16x32_bf16 v[112:115], v[174:177], v[182:185], v[112:115]
	v_mfma_f32_16x16x32_bf16 v[100:103], v[156:159], v[190:193], v[100:103]
	v_mfma_f32_16x16x32_bf16 v[96:99], v[174:177], v[190:193], v[96:99]
	v_mfma_f32_16x16x32_bf16 v[84:87], v[156:159], v[198:201], v[84:87]
	v_mfma_f32_16x16x32_bf16 v[80:83], v[174:177], v[198:201], v[80:83]
	v_mfma_f32_16x16x32_bf16 v[68:71], v[156:159], v[206:209], v[68:71]
	v_mfma_f32_16x16x32_bf16 v[64:67], v[174:177], v[206:209], v[64:67]
	v_mfma_f32_16x16x32_bf16 v[116:119], v[160:163], v[186:189], v[116:119]
	v_mfma_f32_16x16x32_bf16 v[112:115], v[178:181], v[186:189], v[112:115]
	v_mfma_f32_16x16x32_bf16 v[100:103], v[160:163], v[194:197], v[100:103]
	v_mfma_f32_16x16x32_bf16 v[96:99], v[178:181], v[194:197], v[96:99]
	v_mfma_f32_16x16x32_bf16 v[84:87], v[160:163], v[202:205], v[84:87]
	v_mfma_f32_16x16x32_bf16 v[80:83], v[178:181], v[202:205], v[80:83]
	v_mfma_f32_16x16x32_bf16 v[68:71], v[160:163], v[210:213], v[68:71]
	v_mfma_f32_16x16x32_bf16 v[64:67], v[178:181], v[210:213], v[64:67]
	s_setprio 0
	s_barrier
; #define PG8_STAGE(bufoff, gbase, voff) do { _Pragma("unroll") for (int _i = 0; _i < 2; ++_i) \
;         __builtin_amdgcn_global_load_lds((const unsigned*)((const char*)(gbase) + (voff)[_i]), (PG8_LAS unsigned*)(lds + (bufoff) + ldsw + _i * 8192), 16, 0, 0); } while (0)
; #define PG8_LDA(dst, b, h) do { _Pragma("unroll") for (int m = 0; m < 4; ++m) _Pragma("unroll") for (int k = 0; k < 2; ++k) dst[m][k] = *(const PG8_LAS bf16x8*)(lds + PG8_SA(b, h) + aoff + m * 2048 + k * 1024); } while (0)
; #define PG8_MMA(ai, bj, At, Bt) do { __builtin_amdgcn_s_setprio(1); _Pragma("unroll") for (int m = 0; m < 4; ++m) _Pragma("unroll") for (int n = 0; n < 2; ++n) _Pragma("unroll") for (int k = 0; k < 2; ++k) \
;         acc[ai][bj][m][n] = __builtin_amdgcn_mfma_f32_16x16x32_bf16(Bt[n][k], At[m][k], acc[ai][bj][m][n], 0, 0, 0); __builtin_amdgcn_s_setprio(0); } while (0)
; #define PG8_WAIT_V(n) asm volatile("s_waitcnt vmcnt(" #n ")" ::: "memory")
; #define PG8_WAIT_L(n) asm volatile("s_waitcnt lgkmcnt(" #n ")" ::: "memory")
; #define PG8_BAR __builtin_amdgcn_s_barrier()
; #define PG8_SCHED __builtin_amdgcn_sched_barrier(0)
; template <class Epi, class Sched, bool ALIGN_EPI = false, bool SP2 = false>
; __device__ __forceinline__ void gemm_phase(PG8_LAS unsigned char* lds, const Gemm g, const Sched& S, const Epi& E) {
;     ...
;             PG8_LDA(At, 1, 1); PG8_STAGE(PG8_SB(1, 0), b3, voffB); PG8_STAGE(PG8_SB(1, 1), b3 + hstepB, voffB); PG8_STAGE(PG8_SA(1, 0), a3, voffA);
;             PG8_WAIT_V(8); PG8_WAIT_L(0); PG8_BAR; PG8_MMA(1, 0, At, B0); PG8_MMA(1, 1, At, B1); PG8_BAR; PG8_SCHED;
;     ...
;         if constexpr (ALIGN_EPI) { if (wr == 0) PG8_BAR; }
	s_add_i32 s34, s64, s5
	v_lshl_add_u64 v[164:165], v[164:165], 0, s[22:23]
	s_mov_b32 m0, s34
	ds_read_b128 v[182:185], v171 offset:49152
	ds_read_b128 v[186:189], v171 offset:50176
	ds_read_b128 v[190:193], v171 offset:51200
	ds_read_b128 v[194:197], v171 offset:52224
	ds_read_b128 v[198:201], v171 offset:53248
	ds_read_b128 v[202:205], v171 offset:54272
	ds_read_b128 v[206:209], v171 offset:55296
	ds_read_b128 v[210:213], v171 offset:56320
	global_load_lds_dwordx4 v[164:165], off
	s_add_i32 m0, s34, 0x2000
	s_add_u32 s20, s20, 0x80080
	v_lshl_add_u64 v[164:165], v[214:215], 0, s[22:23]
	s_addc_u32 s21, s21, 0
	s_add_i32 s34, s65, s5
	global_load_lds_dwordx4 v[164:165], off
	v_lshl_add_u64 v[164:165], s[20:21], 0, v[138:139]
	s_mov_b32 m0, s34
	s_nop 0
	global_load_lds_dwordx4 v[164:165], off
	v_lshl_add_u64 v[164:165], s[20:21], 0, v[142:143]
	s_add_i32 m0, s34, 0x2000
	s_nop 0
	global_load_lds_dwordx4 v[164:165], off
	v_lshl_add_u64 v[164:165], v[216:217], 0, s[22:23]
	s_mov_b32 m0, s56
	s_nop 0
	global_load_lds_dwordx4 v[164:165], off
	v_lshl_add_u64 v[164:165], v[218:219], 0, s[22:23]
	s_mov_b32 m0, s57
	s_nop 0
	global_load_lds_dwordx4 v[164:165], off
	s_waitcnt vmcnt(8)
	s_waitcnt lgkmcnt(0)
	s_barrier
	s_setprio 1
	v_mfma_f32_16x16x32_bf16 v[60:63], v[128:131], v[182:185], v[60:63]
	v_mfma_f32_16x16x32_bf16 v[56:59], v[148:151], v[182:185], v[56:59]
	v_mfma_f32_16x16x32_bf16 v[44:47], v[128:131], v[190:193], v[44:47]
	v_mfma_f32_16x16x32_bf16 v[40:43], v[148:151], v[190:193], v[40:43]
	v_mfma_f32_16x16x32_bf16 v[28:31], v[128:131], v[198:201], v[28:31]
	v_mfma_f32_16x16x32_bf16 v[24:27], v[148:151], v[198:201], v[24:27]
	v_mfma_f32_16x16x32_bf16 v[12:15], v[128:131], v[206:209], v[12:15]
	v_mfma_f32_16x16x32_bf16 v[8:11], v[148:151], v[206:209], v[8:11]
	v_mfma_f32_16x16x32_bf16 v[60:63], v[132:135], v[186:189], v[60:63]
	v_mfma_f32_16x16x32_bf16 v[56:59], v[152:155], v[186:189], v[56:59]
	v_mfma_f32_16x16x32_bf16 v[44:47], v[132:135], v[194:197], v[44:47]
	v_mfma_f32_16x16x32_bf16 v[40:43], v[152:155], v[194:197], v[40:43]
	v_mfma_f32_16x16x32_bf16 v[28:31], v[132:135], v[202:205], v[28:31]
	v_mfma_f32_16x16x32_bf16 v[24:27], v[152:155], v[202:205], v[24:27]
	v_mfma_f32_16x16x32_bf16 v[12:15], v[132:135], v[210:213], v[12:15]
	v_mfma_f32_16x16x32_bf16 v[8:11], v[152:155], v[210:213], v[8:11]
	s_setprio 0
	s_setprio 1
	v_mfma_f32_16x16x32_bf16 v[52:55], v[156:159], v[182:185], v[52:55]
	v_mfma_f32_16x16x32_bf16 v[48:51], v[174:177], v[182:185], v[48:51]
	v_mfma_f32_16x16x32_bf16 v[36:39], v[156:159], v[190:193], v[36:39]
	v_mfma_f32_16x16x32_bf16 v[32:35], v[174:177], v[190:193], v[32:35]
	v_mfma_f32_16x16x32_bf16 v[20:23], v[156:159], v[198:201], v[20:23]
	v_mfma_f32_16x16x32_bf16 v[16:19], v[174:177], v[198:201], v[16:19]
	v_mfma_f32_16x16x32_bf16 v[4:7], v[156:159], v[206:209], v[4:7]
	v_mfma_f32_16x16x32_bf16 v[0:3], v[174:177], v[206:209], v[0:3]
	v_mfma_f32_16x16x32_bf16 v[52:55], v[160:163], v[186:189], v[52:55]
	v_mfma_f32_16x16x32_bf16 v[48:51], v[178:181], v[186:189], v[48:51]
	v_mfma_f32_16x16x32_bf16 v[36:39], v[160:163], v[194:197], v[36:39]
	v_mfma_f32_16x16x32_bf16 v[32:35], v[178:181], v[194:197], v[32:35]
	v_mfma_f32_16x16x32_bf16 v[20:23], v[160:163], v[202:205], v[20:23]
	v_mfma_f32_16x16x32_bf16 v[16:19], v[178:181], v[202:205], v[16:19]
	v_mfma_f32_16x16x32_bf16 v[4:7], v[160:163], v[210:213], v[4:7]
	v_mfma_f32_16x16x32_bf16 v[0:3], v[178:181], v[210:213], v[0:3]
	s_setprio 0
	s_barrier
	s_add_i32 s63, s63, 2
	s_add_u32 s16, s16, 0x100
	s_addc_u32 s17, s17, 0
	s_add_u32 s61, s61, 0x100
	s_addc_u32 s62, s62, 0
	s_cmp_gt_u32 s63, 29
	s_cbranch_scc0 .LBB0_1363
	s_and_b64 vcc, exec, s[24:25]
	s_cbranch_vccz .LBB0_1366
	s_barrier

; #define PG8_STAGE(bufoff, gbase, voff) do { _Pragma("unroll") for (int _i = 0; _i < 2; ++_i) \
;         __builtin_amdgcn_global_load_lds((const unsigned*)((const char*)(gbase) + (voff)[_i]), (PG8_LAS unsigned*)(lds + (bufoff) + ldsw + _i * 8192), 16, 0, 0); } while (0)
; #define PG8_LDA(dst, b, h) do { _Pragma("unroll") for (int m = 0; m < 4; ++m) _Pragma("unroll") for (int k = 0; k < 2; ++k) dst[m][k] = *(const PG8_LAS bf16x8*)(lds + PG8_SA(b, h) + aoff + m * 2048 + k * 1024); } while (0)
; #define PG8_LDB(dst, b, h) do { _Pragma("unroll") for (int n = 0; n < 2; ++n) _Pragma("unroll") for (int k = 0; k < 2; ++k) dst[n][k] = *(const PG8_LAS bf16x8*)(lds + PG8_SB(b, h) + boff + n * 2048 + k * 1024); } while (0)
; #define PG8_MMA(ai, bj, At, Bt) do { __builtin_amdgcn_s_setprio(1); _Pragma("unroll") for (int m = 0; m < 4; ++m) _Pragma("unroll") for (int n = 0; n < 2; ++n) _Pragma("unroll") for (int k = 0; k < 2; ++k) \
;         acc[ai][bj][m][n] = __builtin_amdgcn_mfma_f32_16x16x32_bf16(Bt[n][k], At[m][k], acc[ai][bj][m][n], 0, 0, 0); __builtin_amdgcn_s_setprio(0); } while (0)
; #define PG8_WAIT_V(n) asm volatile("s_waitcnt vmcnt(" #n ")" ::: "memory")
; template <class Epi, class Sched, bool ALIGN_EPI = false, bool SP2 = false>
; __device__ __forceinline__ void gemm_phase(PG8_LAS unsigned char* lds, const Gemm g, const Sched& S, const Epi& E) {
;     ...
;             const bool last = (t == nt - 2);
;             if constexpr (Epi::HAS_MID) { if (t == E.mid_t) E.mid(acc, cur, wr, wc, fr, fq); }
;             const char* a1 = cA + (size_t)(t + 1) * kstep;
;             const char* a2 = last ? nA : cA + (size_t)(t + 2) * kstep; const char* b2 = last ? nB : cB + (size_t)(t + 2) * kstep;
;             const char* a3 = a2 + kstep; const char* b3 = b2 + kstep;
;             if (last && has_next) S.a_ready(nxt);
;             if constexpr (SP2) {
;             PG8_LDB(B0, 0, 0); PG8_LDB(B1, 0, 1); PG8_SCHED; PG8_LDA(At, 0, 0); PG8_STAGE(PG8_SA(1, 1), a1 + hstepA, voffA);
;             PG8_WAIT_V(8); PG8_WAIT_L(0); PG8_BAR; PG8_MMA(0, 0, At, B0); PG8_MMA(0, 1, At, B1); PG8_BAR; PG8_SCHED;
;             PG8_LDA(At, 0, 1); PG8_STAGE(PG8_SB(0, 0), b2, voffB); PG8_STAGE(PG8_SB(0, 1), b2 + hstepB, voffB); PG8_STAGE(PG8_SA(0, 0), a2, voffA);
;             PG8_WAIT_V(8); PG8_WAIT_L(0); PG8_BAR; PG8_MMA(1, 0, At, B0); PG8_MMA(1, 1, At, B1); PG8_BAR; PG8_SCHED;
.LBB0_1738:
	ds_read_b128 v[144:147], v151
	ds_read_b128 v[154:157], v151 offset:1024
	ds_read_b128 v[158:161], v151 offset:2048
	ds_read_b128 v[162:165], v151 offset:3072
	ds_read_b128 v[166:169], v152
	ds_read_b128 v[170:173], v152 offset:1024
	ds_read_b128 v[174:177], v152 offset:2048
	ds_read_b128 v[178:181], v152 offset:3072
	s_add_u32 s34, s20, 0xfffe0080
	s_addc_u32 s35, s21, -1
	s_cmp_eq_u32 s57, 4
	s_cselect_b32 s39, s13, s35
	s_cselect_b32 s38, s27, s34
	s_cselect_b32 s35, s25, s56
	s_cselect_b32 s34, s52, s53
	s_add_i32 m0, s5, 0xc000
	ds_read_b128 v[182:185], v153
	ds_read_b128 v[186:189], v153 offset:1024
	ds_read_b128 v[190:193], v153 offset:2048
	ds_read_b128 v[194:197], v153 offset:3072
	ds_read_b128 v[198:201], v153 offset:4096
	ds_read_b128 v[202:205], v153 offset:5120
	ds_read_b128 v[206:209], v153 offset:6144
	ds_read_b128 v[210:213], v153 offset:7168
	s_add_u32 s98, s20, 0xfffe0000
	s_addc_u32 s99, s21, -1
	s_mov_b32 m0, s42
	s_nop 0
	global_load_lds_dwordx4 v128, s[98:99]
	s_mov_b32 m0, s43
	s_nop 0
	global_load_lds_dwordx4 v132, s[98:99]
	s_add_i32 m0, s5, 0xc000
	s_nop 0
	global_load_lds_dwordx4 v136, s[20:21]
	s_add_i32 m0, s5, 0xe000
	s_nop 0
	global_load_lds_dwordx4 v138, s[20:21]
	s_waitcnt vmcnt(8)
	s_waitcnt lgkmcnt(0)
	s_barrier
	s_setprio 1
	v_mfma_f32_16x16x32_bf16 v[124:127], v[144:147], v[182:185], v[124:127]
	v_mfma_f32_16x16x32_bf16 v[120:123], v[158:161], v[182:185], v[120:123]
	v_mfma_f32_16x16x32_bf16 v[108:111], v[144:147], v[190:193], v[108:111]
	v_mfma_f32_16x16x32_bf16 v[104:107], v[158:161], v[190:193], v[104:107]
	v_mfma_f32_16x16x32_bf16 v[92:95], v[144:147], v[198:201], v[92:95]
	v_mfma_f32_16x16x32_bf16 v[88:91], v[158:161], v[198:201], v[88:91]
	v_mfma_f32_16x16x32_bf16 v[76:79], v[144:147], v[206:209], v[76:79]
	v_mfma_f32_16x16x32_bf16 v[72:75], v[158:161], v[206:209], v[72:75]
	v_mfma_f32_16x16x32_bf16 v[124:127], v[154:157], v[186:189], v[124:127]
	v_mfma_f32_16x16x32_bf16 v[120:123], v[162:165], v[186:189], v[120:123]
	v_mfma_f32_16x16x32_bf16 v[108:111], v[154:157], v[194:197], v[108:111]
	v_mfma_f32_16x16x32_bf16 v[104:107], v[162:165], v[194:197], v[104:107]
	v_mfma_f32_16x16x32_bf16 v[92:95], v[154:157], v[202:205], v[92:95]
	v_mfma_f32_16x16x32_bf16 v[88:91], v[162:165], v[202:205], v[88:91]
	v_mfma_f32_16x16x32_bf16 v[76:79], v[154:157], v[210:213], v[76:79]
	v_mfma_f32_16x16x32_bf16 v[72:75], v[162:165], v[210:213], v[72:75]
	s_setprio 0
	s_setprio 1
	v_mfma_f32_16x16x32_bf16 v[116:119], v[166:169], v[182:185], v[116:119]
	v_mfma_f32_16x16x32_bf16 v[112:115], v[174:177], v[182:185], v[112:115]
	v_mfma_f32_16x16x32_bf16 v[100:103], v[166:169], v[190:193], v[100:103]
	v_mfma_f32_16x16x32_bf16 v[96:99], v[174:177], v[190:193], v[96:99]
	v_mfma_f32_16x16x32_bf16 v[84:87], v[166:169], v[198:201], v[84:87]
	v_mfma_f32_16x16x32_bf16 v[80:83], v[174:177], v[198:201], v[80:83]
	v_mfma_f32_16x16x32_bf16 v[68:71], v[166:169], v[206:209], v[68:71]
	v_mfma_f32_16x16x32_bf16 v[64:67], v[174:177], v[206:209], v[64:67]
	v_mfma_f32_16x16x32_bf16 v[116:119], v[170:173], v[186:189], v[116:119]
	v_mfma_f32_16x16x32_bf16 v[112:115], v[178:181], v[186:189], v[112:115]
	v_mfma_f32_16x16x32_bf16 v[100:103], v[170:173], v[194:197], v[100:103]
	v_mfma_f32_16x16x32_bf16 v[96:99], v[178:181], v[194:197], v[96:99]
	v_mfma_f32_16x16x32_bf16 v[84:87], v[170:173], v[202:205], v[84:87]
	v_mfma_f32_16x16x32_bf16 v[80:83], v[178:181], v[202:205], v[80:83]
	v_mfma_f32_16x16x32_bf16 v[68:71], v[170:173], v[210:213], v[68:71]
	v_mfma_f32_16x16x32_bf16 v[64:67], v[178:181], v[210:213], v[64:67]
	s_setprio 0
	s_barrier
	s_add_i32 s58, s47, s4
	s_mov_b32 m0, s58
	ds_read_b128 v[182:185], v153 offset:16384
	ds_read_b128 v[186:189], v153 offset:17408
	ds_read_b128 v[190:193], v153 offset:18432
	ds_read_b128 v[194:197], v153 offset:19456
	ds_read_b128 v[198:201], v153 offset:20480
	ds_read_b128 v[202:205], v153 offset:21504
	ds_read_b128 v[206:209], v153 offset:22528
	ds_read_b128 v[210:213], v153 offset:23552
	global_load_lds_dwordx4 v130, s[34:35]
	s_add_i32 m0, s58, 0x2000
	s_add_u32 s58, s34, 0x20000
	s_addc_u32 s59, s35, 0
	s_add_i32 s60, s50, s4
	global_load_lds_dwordx4 v134, s[34:35]
	s_mov_b32 m0, s60
	s_nop 0
	global_load_lds_dwordx4 v130, s[58:59]
	s_add_i32 m0, s60, 0x2000
	s_nop 0
	global_load_lds_dwordx4 v134, s[58:59]
	s_waitcnt vmcnt(6)
	s_waitcnt lgkmcnt(0)
	s_barrier
	s_setprio 1
	v_mfma_f32_16x16x32_bf16 v[60:63], v[144:147], v[182:185], v[60:63]
	v_mfma_f32_16x16x32_bf16 v[56:59], v[158:161], v[182:185], v[56:59]
	v_mfma_f32_16x16x32_bf16 v[44:47], v[144:147], v[190:193], v[44:47]
	v_mfma_f32_16x16x32_bf16 v[40:43], v[158:161], v[190:193], v[40:43]
	v_mfma_f32_16x16x32_bf16 v[28:31], v[144:147], v[198:201], v[28:31]
	v_mfma_f32_16x16x32_bf16 v[24:27], v[158:161], v[198:201], v[24:27]
	v_mfma_f32_16x16x32_bf16 v[12:15], v[144:147], v[206:209], v[12:15]
	v_mfma_f32_16x16x32_bf16 v[8:11], v[158:161], v[206:209], v[8:11]
	v_mfma_f32_16x16x32_bf16 v[60:63], v[154:157], v[186:189], v[60:63]
	v_mfma_f32_16x16x32_bf16 v[56:59], v[162:165], v[186:189], v[56:59]
	v_mfma_f32_16x16x32_bf16 v[44:47], v[154:157], v[194:197], v[44:47]
	v_mfma_f32_16x16x32_bf16 v[40:43], v[162:165], v[194:197], v[40:43]
	v_mfma_f32_16x16x32_bf16 v[28:31], v[154:157], v[202:205], v[28:31]
	v_mfma_f32_16x16x32_bf16 v[24:27], v[162:165], v[202:205], v[24:27]
	v_mfma_f32_16x16x32_bf16 v[12:15], v[154:157], v[210:213], v[12:15]
	v_mfma_f32_16x16x32_bf16 v[8:11], v[162:165], v[210:213], v[8:11]
	s_setprio 0
	s_setprio 1
	v_mfma_f32_16x16x32_bf16 v[52:55], v[166:169], v[182:185], v[52:55]
	v_mfma_f32_16x16x32_bf16 v[48:51], v[174:177], v[182:185], v[48:51]
	v_mfma_f32_16x16x32_bf16 v[36:39], v[166:169], v[190:193], v[36:39]
	v_mfma_f32_16x16x32_bf16 v[32:35], v[174:177], v[190:193], v[32:35]
	v_mfma_f32_16x16x32_bf16 v[20:23], v[166:169], v[198:201], v[20:23]
	v_mfma_f32_16x16x32_bf16 v[16:19], v[174:177], v[198:201], v[16:19]
	v_mfma_f32_16x16x32_bf16 v[4:7], v[166:169], v[206:209], v[4:7]
	v_mfma_f32_16x16x32_bf16 v[0:3], v[174:177], v[206:209], v[0:3]
	v_mfma_f32_16x16x32_bf16 v[52:55], v[170:173], v[186:189], v[52:55]
	v_mfma_f32_16x16x32_bf16 v[48:51], v[178:181], v[186:189], v[48:51]
	v_mfma_f32_16x16x32_bf16 v[36:39], v[170:173], v[194:197], v[36:39]
	v_mfma_f32_16x16x32_bf16 v[32:35], v[178:181], v[194:197], v[32:35]
	v_mfma_f32_16x16x32_bf16 v[20:23], v[170:173], v[202:205], v[20:23]
	v_mfma_f32_16x16x32_bf16 v[16:19], v[178:181], v[202:205], v[16:19]
	v_mfma_f32_16x16x32_bf16 v[4:7], v[170:173], v[210:213], v[4:7]
	v_mfma_f32_16x16x32_bf16 v[0:3], v[178:181], v[210:213], v[0:3]
	s_setprio 0
	s_barrier
; #define PG8_STAGE(bufoff, gbase, voff) do { _Pragma("unroll") for (int _i = 0; _i < 2; ++_i) \
;         __builtin_amdgcn_global_load_lds((const unsigned*)((const char*)(gbase) + (voff)[_i]), (PG8_LAS unsigned*)(lds + (bufoff) + ldsw + _i * 8192), 16, 0, 0); } while (0)
; #define PG8_LDA(dst, b, h) do { _Pragma("unroll") for (int m = 0; m < 4; ++m) _Pragma("unroll") for (int k = 0; k < 2; ++k) dst[m][k] = *(const PG8_LAS bf16x8*)(lds + PG8_SA(b, h) + aoff + m * 2048 + k * 1024); } while (0)
; #define PG8_LDB(dst, b, h) do { _Pragma("unroll") for (int n = 0; n < 2; ++n) _Pragma("unroll") for (int k = 0; k < 2; ++k) dst[n][k] = *(const PG8_LAS bf16x8*)(lds + PG8_SB(b, h) + boff + n * 2048 + k * 1024); } while (0)
; #define PG8_MMA(ai, bj, At, Bt) do { __builtin_amdgcn_s_setprio(1); _Pragma("unroll") for (int m = 0; m < 4; ++m) _Pragma("unroll") for (int n = 0; n < 2; ++n) _Pragma("unroll") for (int k = 0; k < 2; ++k) \
;         acc[ai][bj][m][n] = __builtin_amdgcn_mfma_f32_16x16x32_bf16(Bt[n][k], At[m][k], acc[ai][bj][m][n], 0, 0, 0); __builtin_amdgcn_s_setprio(0); } while (0)
; #define PG8_WAIT_V(n) asm volatile("s_waitcnt vmcnt(" #n ")" ::: "memory")
; #define PG8_WAIT_L(n) asm volatile("s_waitcnt lgkmcnt(" #n ")" ::: "memory")
; #define PG8_BAR __builtin_amdgcn_s_barrier()
; #define PG8_SCHED __builtin_amdgcn_sched_barrier(0)
; template <class Epi, class Sched, bool ALIGN_EPI = false, bool SP2 = false>
; __device__ __forceinline__ void gemm_phase(PG8_LAS unsigned char* lds, const Gemm g, const Sched& S, const Epi& E) {
;     ...
;             PG8_LDB(B0, 1, 0); PG8_LDB(B1, 1, 1); PG8_SCHED; PG8_LDA(At, 1, 0); PG8_STAGE(PG8_SA(0, 1), a2 + hstepA, voffA);
;             PG8_WAIT_V(8); PG8_WAIT_L(0); PG8_BAR; PG8_MMA(0, 0, At, B0); PG8_MMA(0, 1, At, B1); PG8_BAR; PG8_SCHED;
;             PG8_LDA(At, 1, 1); PG8_STAGE(PG8_SB(1, 0), b3, voffB); PG8_STAGE(PG8_SB(1, 1), b3 + hstepB, voffB); PG8_STAGE(PG8_SA(1, 0), a3, voffA);
;             PG8_WAIT_V(8); PG8_WAIT_L(0); PG8_BAR; PG8_MMA(1, 0, At, B0); PG8_MMA(1, 1, At, B1); PG8_BAR; PG8_SCHED;
;     ...
;         if constexpr (ALIGN_EPI) { if (wr == 0) PG8_BAR; }
	s_add_i32 s58, 0, 0x18000
	s_add_i32 s59, 0, 0x1c000
	v_add_u32_e32 v162, s58, v150
	v_add_u32_e32 v178, s59, v150
	ds_read_b128 v[144:147], v162
	ds_read_b128 v[154:157], v162 offset:1024
	ds_read_b128 v[158:161], v162 offset:2048
	ds_read_b128 v[162:165], v162 offset:3072
	ds_read_b128 v[166:169], v178
	ds_read_b128 v[170:173], v178 offset:1024
	ds_read_b128 v[174:177], v178 offset:2048
	ds_read_b128 v[178:181], v178 offset:3072
	s_mov_b64 s[100:101], s[38:39]
	s_add_u32 s38, s38, 0x20000
	s_addc_u32 s39, s39, 0
	s_mov_b32 m0, s7
	ds_read_b128 v[182:185], v153 offset:32768
	ds_read_b128 v[186:189], v153 offset:33792
	ds_read_b128 v[190:193], v153 offset:34816
	ds_read_b128 v[194:197], v153 offset:35840
	ds_read_b128 v[198:201], v153 offset:36864
	ds_read_b128 v[202:205], v153 offset:37888
	ds_read_b128 v[206:209], v153 offset:38912
	ds_read_b128 v[210:213], v153 offset:39936
	s_mov_b32 m0, s5
	s_nop 0
	global_load_lds_dwordx4 v128, s[100:101]
	s_mov_b32 m0, s6
	s_nop 0
	global_load_lds_dwordx4 v132, s[100:101]
	s_mov_b32 m0, s7
	s_nop 0
	global_load_lds_dwordx4 v128, s[38:39]
	s_mov_b32 m0, s33
	s_nop 0
	global_load_lds_dwordx4 v132, s[38:39]
	s_waitcnt vmcnt(8)
	s_waitcnt lgkmcnt(0)
	s_barrier
	s_setprio 1
	v_mfma_f32_16x16x32_bf16 v[124:127], v[144:147], v[182:185], v[124:127]
	v_mfma_f32_16x16x32_bf16 v[120:123], v[158:161], v[182:185], v[120:123]
	v_mfma_f32_16x16x32_bf16 v[108:111], v[144:147], v[190:193], v[108:111]
	v_mfma_f32_16x16x32_bf16 v[104:107], v[158:161], v[190:193], v[104:107]
	v_mfma_f32_16x16x32_bf16 v[92:95], v[144:147], v[198:201], v[92:95]
	v_mfma_f32_16x16x32_bf16 v[88:91], v[158:161], v[198:201], v[88:91]
	v_mfma_f32_16x16x32_bf16 v[76:79], v[144:147], v[206:209], v[76:79]
	v_mfma_f32_16x16x32_bf16 v[72:75], v[158:161], v[206:209], v[72:75]
	v_mfma_f32_16x16x32_bf16 v[124:127], v[154:157], v[186:189], v[124:127]
	v_mfma_f32_16x16x32_bf16 v[120:123], v[162:165], v[186:189], v[120:123]
	v_mfma_f32_16x16x32_bf16 v[108:111], v[154:157], v[194:197], v[108:111]
	v_mfma_f32_16x16x32_bf16 v[104:107], v[162:165], v[194:197], v[104:107]
	v_mfma_f32_16x16x32_bf16 v[92:95], v[154:157], v[202:205], v[92:95]
	v_mfma_f32_16x16x32_bf16 v[88:91], v[162:165], v[202:205], v[88:91]
	v_mfma_f32_16x16x32_bf16 v[76:79], v[154:157], v[210:213], v[76:79]
	v_mfma_f32_16x16x32_bf16 v[72:75], v[162:165], v[210:213], v[72:75]
	s_setprio 0
	s_setprio 1
	v_mfma_f32_16x16x32_bf16 v[116:119], v[166:169], v[182:185], v[116:119]
	v_mfma_f32_16x16x32_bf16 v[112:115], v[174:177], v[182:185], v[112:115]
	v_mfma_f32_16x16x32_bf16 v[100:103], v[166:169], v[190:193], v[100:103]
	v_mfma_f32_16x16x32_bf16 v[96:99], v[174:177], v[190:193], v[96:99]
	v_mfma_f32_16x16x32_bf16 v[84:87], v[166:169], v[198:201], v[84:87]
	v_mfma_f32_16x16x32_bf16 v[80:83], v[174:177], v[198:201], v[80:83]
	v_mfma_f32_16x16x32_bf16 v[68:71], v[166:169], v[206:209], v[68:71]
	v_mfma_f32_16x16x32_bf16 v[64:67], v[174:177], v[206:209], v[64:67]
	v_mfma_f32_16x16x32_bf16 v[116:119], v[170:173], v[186:189], v[116:119]
	v_mfma_f32_16x16x32_bf16 v[112:115], v[178:181], v[186:189], v[112:115]
	v_mfma_f32_16x16x32_bf16 v[100:103], v[170:173], v[194:197], v[100:103]
	v_mfma_f32_16x16x32_bf16 v[96:99], v[178:181], v[194:197], v[96:99]
	v_mfma_f32_16x16x32_bf16 v[84:87], v[170:173], v[202:205], v[84:87]
	v_mfma_f32_16x16x32_bf16 v[80:83], v[178:181], v[202:205], v[80:83]
	v_mfma_f32_16x16x32_bf16 v[68:71], v[170:173], v[210:213], v[68:71]
	v_mfma_f32_16x16x32_bf16 v[64:67], v[178:181], v[210:213], v[64:67]
	s_setprio 0
	s_barrier
	s_add_i32 s38, s58, s4
	s_add_u32 s98, s34, 0x80
	s_addc_u32 s99, s35, 0
	s_mov_b32 m0, s38
	ds_read_b128 v[182:185], v153 offset:49152
	ds_read_b128 v[186:189], v153 offset:50176
	ds_read_b128 v[190:193], v153 offset:51200
	ds_read_b128 v[194:197], v153 offset:52224
	ds_read_b128 v[198:201], v153 offset:53248
	ds_read_b128 v[202:205], v153 offset:54272
	ds_read_b128 v[206:209], v153 offset:55296
	ds_read_b128 v[210:213], v153 offset:56320
	global_load_lds_dwordx4 v130, s[98:99]
	s_add_i32 m0, s38, 0x2000
	s_add_u32 s34, s34, 0x20080
	s_addc_u32 s35, s35, 0
	s_add_i32 s38, s59, s4
	global_load_lds_dwordx4 v134, s[98:99]
	s_mov_b32 m0, s38
	s_nop 0
	global_load_lds_dwordx4 v130, s[34:35]
	s_add_i32 m0, s38, 0x2000
	s_nop 0
	global_load_lds_dwordx4 v134, s[34:35]
	s_waitcnt vmcnt(6)
	s_waitcnt lgkmcnt(0)
	s_barrier
	s_setprio 1
	v_mfma_f32_16x16x32_bf16 v[60:63], v[144:147], v[182:185], v[60:63]
	v_mfma_f32_16x16x32_bf16 v[56:59], v[158:161], v[182:185], v[56:59]
	v_mfma_f32_16x16x32_bf16 v[44:47], v[144:147], v[190:193], v[44:47]
	v_mfma_f32_16x16x32_bf16 v[40:43], v[158:161], v[190:193], v[40:43]
	v_mfma_f32_16x16x32_bf16 v[28:31], v[144:147], v[198:201], v[28:31]
	v_mfma_f32_16x16x32_bf16 v[24:27], v[158:161], v[198:201], v[24:27]
	v_mfma_f32_16x16x32_bf16 v[12:15], v[144:147], v[206:209], v[12:15]
	v_mfma_f32_16x16x32_bf16 v[8:11], v[158:161], v[206:209], v[8:11]
	v_mfma_f32_16x16x32_bf16 v[60:63], v[154:157], v[186:189], v[60:63]
	v_mfma_f32_16x16x32_bf16 v[56:59], v[162:165], v[186:189], v[56:59]
	v_mfma_f32_16x16x32_bf16 v[44:47], v[154:157], v[194:197], v[44:47]
	v_mfma_f32_16x16x32_bf16 v[40:43], v[162:165], v[194:197], v[40:43]
	v_mfma_f32_16x16x32_bf16 v[28:31], v[154:157], v[202:205], v[28:31]
	v_mfma_f32_16x16x32_bf16 v[24:27], v[162:165], v[202:205], v[24:27]
	v_mfma_f32_16x16x32_bf16 v[12:15], v[154:157], v[210:213], v[12:15]
	v_mfma_f32_16x16x32_bf16 v[8:11], v[162:165], v[210:213], v[8:11]
	s_setprio 0
	s_setprio 1
	v_mfma_f32_16x16x32_bf16 v[52:55], v[166:169], v[182:185], v[52:55]
	v_mfma_f32_16x16x32_bf16 v[48:51], v[174:177], v[182:185], v[48:51]
	v_mfma_f32_16x16x32_bf16 v[36:39], v[166:169], v[190:193], v[36:39]
	v_mfma_f32_16x16x32_bf16 v[32:35], v[174:177], v[190:193], v[32:35]
	v_mfma_f32_16x16x32_bf16 v[20:23], v[166:169], v[198:201], v[20:23]
	v_mfma_f32_16x16x32_bf16 v[16:19], v[174:177], v[198:201], v[16:19]
	v_mfma_f32_16x16x32_bf16 v[4:7], v[166:169], v[206:209], v[4:7]
	v_mfma_f32_16x16x32_bf16 v[0:3], v[174:177], v[206:209], v[0:3]
	v_mfma_f32_16x16x32_bf16 v[52:55], v[170:173], v[186:189], v[52:55]
	v_mfma_f32_16x16x32_bf16 v[48:51], v[178:181], v[186:189], v[48:51]
	v_mfma_f32_16x16x32_bf16 v[36:39], v[170:173], v[194:197], v[36:39]
	v_mfma_f32_16x16x32_bf16 v[32:35], v[178:181], v[194:197], v[32:35]
	v_mfma_f32_16x16x32_bf16 v[20:23], v[170:173], v[202:205], v[20:23]
	v_mfma_f32_16x16x32_bf16 v[16:19], v[178:181], v[202:205], v[16:19]
	v_mfma_f32_16x16x32_bf16 v[4:7], v[170:173], v[210:213], v[4:7]
	v_mfma_f32_16x16x32_bf16 v[0:3], v[178:181], v[210:213], v[0:3]
	s_setprio 0
	s_barrier
	s_add_i32 s57, s57, 2
	s_add_u32 s20, s20, 0x100
	s_addc_u32 s21, s21, 0
	s_add_u32 s53, s53, 0x100
	s_addc_u32 s56, s56, 0
	s_cmp_gt_u32 s57, 5
	s_cbranch_scc0 .LBB0_1738
	s_and_b64 vcc, exec, s[22:23]
	s_cbranch_vccz .LBB0_1741
	s_barrier

; #define PG8_STAGE(bufoff, gbase, voff) do { _Pragma("unroll") for (int _i = 0; _i < 2; ++_i) \
;         __builtin_amdgcn_global_load_lds((const unsigned*)((const char*)(gbase) + (voff)[_i]), (PG8_LAS unsigned*)(lds + (bufoff) + ldsw + _i * 8192), 16, 0, 0); } while (0)
; #define PG8_LDA(dst, b, h) do { _Pragma("unroll") for (int m = 0; m < 4; ++m) _Pragma("unroll") for (int k = 0; k < 2; ++k) dst[m][k] = *(const PG8_LAS bf16x8*)(lds + PG8_SA(b, h) + aoff + m * 2048 + k * 1024); } while (0)
; #define PG8_LDB(dst, b, h) do { _Pragma("unroll") for (int n = 0; n < 2; ++n) _Pragma("unroll") for (int k = 0; k < 2; ++k) dst[n][k] = *(const PG8_LAS bf16x8*)(lds + PG8_SB(b, h) + boff + n * 2048 + k * 1024); } while (0)
; #define PG8_MMA(ai, bj, At, Bt) do { __builtin_amdgcn_s_setprio(1); _Pragma("unroll") for (int m = 0; m < 4; ++m) _Pragma("unroll") for (int n = 0; n < 2; ++n) _Pragma("unroll") for (int k = 0; k < 2; ++k) \
;         acc[ai][bj][m][n] = __builtin_amdgcn_mfma_f32_16x16x32_bf16(Bt[n][k], At[m][k], acc[ai][bj][m][n], 0, 0, 0); __builtin_amdgcn_s_setprio(0); } while (0)
; #define PG8_WAIT_V(n) asm volatile("s_waitcnt vmcnt(" #n ")" ::: "memory")
; template <class Epi, class Sched, bool ALIGN_EPI = false, bool SP2 = false>
; __device__ __forceinline__ void gemm_phase(PG8_LAS unsigned char* lds, const Gemm g, const Sched& S, const Epi& E) {
;     ...
;             const bool last = (t == nt - 2);
;             if constexpr (Epi::HAS_MID) { if (t == E.mid_t) E.mid(acc, cur, wr, wc, fr, fq); }
;             const char* a1 = cA + (size_t)(t + 1) * kstep;
;             const char* a2 = last ? nA : cA + (size_t)(t + 2) * kstep; const char* b2 = last ? nB : cB + (size_t)(t + 2) * kstep;
;             const char* a3 = a2 + kstep; const char* b3 = b2 + kstep;
;             if (last && has_next) S.a_ready(nxt);
;             if constexpr (SP2) {
;             PG8_LDB(B0, 0, 0); PG8_LDB(B1, 0, 1); PG8_SCHED; PG8_LDA(At, 0, 0); PG8_STAGE(PG8_SA(1, 1), a1 + hstepA, voffA);
;             PG8_WAIT_V(8); PG8_WAIT_L(0); PG8_BAR; PG8_MMA(0, 0, At, B0); PG8_MMA(0, 1, At, B1); PG8_BAR; PG8_SCHED;
;             PG8_LDA(At, 0, 1); PG8_STAGE(PG8_SB(0, 0), b2, voffB); PG8_STAGE(PG8_SB(0, 1), b2 + hstepB, voffB); PG8_STAGE(PG8_SA(0, 0), a2, voffA);
;             PG8_WAIT_V(8); PG8_WAIT_L(0); PG8_BAR; PG8_MMA(1, 0, At, B0); PG8_MMA(1, 1, At, B1); PG8_BAR; PG8_SCHED;
.Lp7_full_loop:
.LBB0_1824:
	ds_read_b128 v[144:147], v151
	ds_read_b128 v[156:159], v151 offset:1024
	ds_read_b128 v[160:163], v151 offset:2048
	ds_read_b128 v[164:167], v151 offset:3072
	ds_read_b128 v[168:171], v152
	ds_read_b128 v[172:175], v152 offset:1024
	ds_read_b128 v[176:179], v152 offset:2048
	ds_read_b128 v[180:183], v152 offset:3072
	s_add_u32 s34, s30, 0xfff80080
	s_addc_u32 s35, s31, -1
	s_cmp_eq_u32 s62, 28
	s_cselect_b32 s39, s21, s35
	s_cselect_b32 s38, s25, s34
	s_cselect_b32 s35, s23, s61
	s_cselect_b32 s34, s59, s60
	ds_read_b128 v[184:187], v153
	ds_read_b128 v[188:191], v153 offset:1024
	ds_read_b128 v[192:195], v153 offset:2048
	ds_read_b128 v[196:199], v153 offset:3072
	ds_read_b128 v[200:203], v153 offset:4096
	ds_read_b128 v[204:207], v153 offset:5120
	ds_read_b128 v[208:211], v153 offset:6144
	ds_read_b128 v[212:215], v153 offset:7168
	s_add_u32 s98, s30, 0xfff80000
	s_addc_u32 s99, s31, -1
	s_mov_b32 m0, s46
	s_nop 0
	global_load_lds_dwordx4 v134, s[98:99]
	s_mov_b32 m0, s47
	s_nop 0
	global_load_lds_dwordx4 v130, s[98:99]
	s_add_i32 m0, s6, 0xc000
	s_nop 0
	global_load_lds_dwordx4 v136, s[30:31]
	s_add_i32 m0, s6, 0xe000
	s_nop 0
	global_load_lds_dwordx4 v138, s[30:31]
	s_waitcnt vmcnt(8)
	s_waitcnt lgkmcnt(0)
	s_barrier
	s_setprio 1
	v_mfma_f32_16x16x32_bf16 v[124:127], v[144:147], v[184:187], v[124:127]
	v_mfma_f32_16x16x32_bf16 v[116:119], v[160:163], v[184:187], v[116:119]
	v_mfma_f32_16x16x32_bf16 v[108:111], v[144:147], v[192:195], v[108:111]
	v_mfma_f32_16x16x32_bf16 v[100:103], v[160:163], v[192:195], v[100:103]
	v_mfma_f32_16x16x32_bf16 v[92:95], v[144:147], v[200:203], v[92:95]
	v_mfma_f32_16x16x32_bf16 v[84:87], v[160:163], v[200:203], v[84:87]
	v_mfma_f32_16x16x32_bf16 v[76:79], v[144:147], v[208:211], v[76:79]
	v_mfma_f32_16x16x32_bf16 v[68:71], v[160:163], v[208:211], v[68:71]
	v_mfma_f32_16x16x32_bf16 v[124:127], v[156:159], v[188:191], v[124:127]
	v_mfma_f32_16x16x32_bf16 v[116:119], v[164:167], v[188:191], v[116:119]
	v_mfma_f32_16x16x32_bf16 v[108:111], v[156:159], v[196:199], v[108:111]
	v_mfma_f32_16x16x32_bf16 v[100:103], v[164:167], v[196:199], v[100:103]
	v_mfma_f32_16x16x32_bf16 v[92:95], v[156:159], v[204:207], v[92:95]
	v_mfma_f32_16x16x32_bf16 v[84:87], v[164:167], v[204:207], v[84:87]
	v_mfma_f32_16x16x32_bf16 v[76:79], v[156:159], v[212:215], v[76:79]
	v_mfma_f32_16x16x32_bf16 v[68:71], v[164:167], v[212:215], v[68:71]
	s_setprio 0
	s_setprio 1
	v_mfma_f32_16x16x32_bf16 v[120:123], v[168:171], v[184:187], v[120:123]
	v_mfma_f32_16x16x32_bf16 v[112:115], v[176:179], v[184:187], v[112:115]
	v_mfma_f32_16x16x32_bf16 v[104:107], v[168:171], v[192:195], v[104:107]
	v_mfma_f32_16x16x32_bf16 v[96:99], v[176:179], v[192:195], v[96:99]
	v_mfma_f32_16x16x32_bf16 v[88:91], v[168:171], v[200:203], v[88:91]
	v_mfma_f32_16x16x32_bf16 v[80:83], v[176:179], v[200:203], v[80:83]
	v_mfma_f32_16x16x32_bf16 v[72:75], v[168:171], v[208:211], v[72:75]
	v_mfma_f32_16x16x32_bf16 v[64:67], v[176:179], v[208:211], v[64:67]
	v_mfma_f32_16x16x32_bf16 v[120:123], v[172:175], v[188:191], v[120:123]
	v_mfma_f32_16x16x32_bf16 v[112:115], v[180:183], v[188:191], v[112:115]
	v_mfma_f32_16x16x32_bf16 v[104:107], v[172:175], v[196:199], v[104:107]
	v_mfma_f32_16x16x32_bf16 v[96:99], v[180:183], v[196:199], v[96:99]
	v_mfma_f32_16x16x32_bf16 v[88:91], v[172:175], v[204:207], v[88:91]
	v_mfma_f32_16x16x32_bf16 v[80:83], v[180:183], v[204:207], v[80:83]
	v_mfma_f32_16x16x32_bf16 v[72:75], v[172:175], v[212:215], v[72:75]
	v_mfma_f32_16x16x32_bf16 v[64:67], v[180:183], v[212:215], v[64:67]
	s_setprio 0
	s_barrier
	s_add_i32 s63, s53, s4
	s_mov_b32 m0, s63
	ds_read_b128 v[184:187], v153 offset:16384
	ds_read_b128 v[188:191], v153 offset:17408
	ds_read_b128 v[192:195], v153 offset:18432
	ds_read_b128 v[196:199], v153 offset:19456
	ds_read_b128 v[200:203], v153 offset:20480
	ds_read_b128 v[204:207], v153 offset:21504
	ds_read_b128 v[208:211], v153 offset:22528
	ds_read_b128 v[212:215], v153 offset:23552
	global_load_lds_dwordx4 v132, s[34:35]
	s_add_i32 m0, s63, 0x2000
	s_add_u32 s64, s34, 0x80000
	s_addc_u32 s65, s35, 0
	s_add_i32 s63, s54, s4
	global_load_lds_dwordx4 v128, s[34:35]
	s_mov_b32 m0, s63
	s_nop 0
	global_load_lds_dwordx4 v132, s[64:65]
	s_add_i32 m0, s63, 0x2000
	s_nop 0
	global_load_lds_dwordx4 v128, s[64:65]
	s_waitcnt vmcnt(6)
	s_waitcnt lgkmcnt(0)
	s_barrier
	s_setprio 1
	v_mfma_f32_16x16x32_bf16 v[60:63], v[144:147], v[184:187], v[60:63]
	v_mfma_f32_16x16x32_bf16 v[52:55], v[160:163], v[184:187], v[52:55]
	v_mfma_f32_16x16x32_bf16 v[44:47], v[144:147], v[192:195], v[44:47]
	v_mfma_f32_16x16x32_bf16 v[36:39], v[160:163], v[192:195], v[36:39]
	v_mfma_f32_16x16x32_bf16 v[28:31], v[144:147], v[200:203], v[28:31]
	v_mfma_f32_16x16x32_bf16 v[20:23], v[160:163], v[200:203], v[20:23]
	v_mfma_f32_16x16x32_bf16 v[12:15], v[144:147], v[208:211], v[12:15]
	v_mfma_f32_16x16x32_bf16 v[4:7], v[160:163], v[208:211], v[4:7]
	v_mfma_f32_16x16x32_bf16 v[60:63], v[156:159], v[188:191], v[60:63]
	v_mfma_f32_16x16x32_bf16 v[52:55], v[164:167], v[188:191], v[52:55]
	v_mfma_f32_16x16x32_bf16 v[44:47], v[156:159], v[196:199], v[44:47]
	v_mfma_f32_16x16x32_bf16 v[36:39], v[164:167], v[196:199], v[36:39]
	v_mfma_f32_16x16x32_bf16 v[28:31], v[156:159], v[204:207], v[28:31]
	v_mfma_f32_16x16x32_bf16 v[20:23], v[164:167], v[204:207], v[20:23]
	v_mfma_f32_16x16x32_bf16 v[12:15], v[156:159], v[212:215], v[12:15]
	v_mfma_f32_16x16x32_bf16 v[4:7], v[164:167], v[212:215], v[4:7]
	s_setprio 0
	s_setprio 1
	v_mfma_f32_16x16x32_bf16 v[56:59], v[168:171], v[184:187], v[56:59]
	v_mfma_f32_16x16x32_bf16 v[48:51], v[176:179], v[184:187], v[48:51]
	v_mfma_f32_16x16x32_bf16 v[40:43], v[168:171], v[192:195], v[40:43]
	v_mfma_f32_16x16x32_bf16 v[32:35], v[176:179], v[192:195], v[32:35]
	v_mfma_f32_16x16x32_bf16 v[24:27], v[168:171], v[200:203], v[24:27]
	v_mfma_f32_16x16x32_bf16 v[16:19], v[176:179], v[200:203], v[16:19]
	v_mfma_f32_16x16x32_bf16 v[8:11], v[168:171], v[208:211], v[8:11]
	v_mfma_f32_16x16x32_bf16 v[0:3], v[176:179], v[208:211], v[0:3]
	v_mfma_f32_16x16x32_bf16 v[56:59], v[172:175], v[188:191], v[56:59]
	v_mfma_f32_16x16x32_bf16 v[48:51], v[180:183], v[188:191], v[48:51]
	v_mfma_f32_16x16x32_bf16 v[40:43], v[172:175], v[196:199], v[40:43]
	v_mfma_f32_16x16x32_bf16 v[32:35], v[180:183], v[196:199], v[32:35]
	v_mfma_f32_16x16x32_bf16 v[24:27], v[172:175], v[204:207], v[24:27]
	v_mfma_f32_16x16x32_bf16 v[16:19], v[180:183], v[204:207], v[16:19]
	v_mfma_f32_16x16x32_bf16 v[8:11], v[172:175], v[212:215], v[8:11]
	v_mfma_f32_16x16x32_bf16 v[0:3], v[180:183], v[212:215], v[0:3]
	s_setprio 0
	s_barrier
; #define PG8_STAGE(bufoff, gbase, voff) do { _Pragma("unroll") for (int _i = 0; _i < 2; ++_i) \
;         __builtin_amdgcn_global_load_lds((const unsigned*)((const char*)(gbase) + (voff)[_i]), (PG8_LAS unsigned*)(lds + (bufoff) + ldsw + _i * 8192), 16, 0, 0); } while (0)
; #define PG8_LDA(dst, b, h) do { _Pragma("unroll") for (int m = 0; m < 4; ++m) _Pragma("unroll") for (int k = 0; k < 2; ++k) dst[m][k] = *(const PG8_LAS bf16x8*)(lds + PG8_SA(b, h) + aoff + m * 2048 + k * 1024); } while (0)
; #define PG8_LDB(dst, b, h) do { _Pragma("unroll") for (int n = 0; n < 2; ++n) _Pragma("unroll") for (int k = 0; k < 2; ++k) dst[n][k] = *(const PG8_LAS bf16x8*)(lds + PG8_SB(b, h) + boff + n * 2048 + k * 1024); } while (0)
; #define PG8_MMA(ai, bj, At, Bt) do { __builtin_amdgcn_s_setprio(1); _Pragma("unroll") for (int m = 0; m < 4; ++m) _Pragma("unroll") for (int n = 0; n < 2; ++n) _Pragma("unroll") for (int k = 0; k < 2; ++k) \
;         acc[ai][bj][m][n] = __builtin_amdgcn_mfma_f32_16x16x32_bf16(Bt[n][k], At[m][k], acc[ai][bj][m][n], 0, 0, 0); __builtin_amdgcn_s_setprio(0); } while (0)
; #define PG8_WAIT_V(n) asm volatile("s_waitcnt vmcnt(" #n ")" ::: "memory")
; #define PG8_WAIT_L(n) asm volatile("s_waitcnt lgkmcnt(" #n ")" ::: "memory")
; #define PG8_BAR __builtin_amdgcn_s_barrier()
; #define PG8_SCHED __builtin_amdgcn_sched_barrier(0)
; template <class Epi, class Sched, bool ALIGN_EPI = false, bool SP2 = false>
; __device__ __forceinline__ void gemm_phase(PG8_LAS unsigned char* lds, const Gemm g, const Sched& S, const Epi& E) {
;     ...
;             PG8_LDB(B0, 1, 0); PG8_LDB(B1, 1, 1); PG8_SCHED; PG8_LDA(At, 1, 0); PG8_STAGE(PG8_SA(0, 1), a2 + hstepA, voffA);
;             PG8_WAIT_V(8); PG8_WAIT_L(0); PG8_BAR; PG8_MMA(0, 0, At, B0); PG8_MMA(0, 1, At, B1); PG8_BAR; PG8_SCHED;
;             PG8_LDA(At, 1, 1); PG8_STAGE(PG8_SB(1, 0), b3, voffB); PG8_STAGE(PG8_SB(1, 1), b3 + hstepB, voffB); PG8_STAGE(PG8_SA(1, 0), a3, voffA);
;             PG8_WAIT_V(8); PG8_WAIT_L(0); PG8_BAR; PG8_MMA(1, 0, At, B0); PG8_MMA(1, 1, At, B1); PG8_BAR; PG8_SCHED;
	s_add_i32 s63, 0, 0x18000
	v_add_u32_e32 v155, s63, v150
	s_add_i32 s64, 0, 0x1c000
	ds_read_b128 v[144:147], v155
	ds_read_b128 v[156:159], v155 offset:1024
	ds_read_b128 v[160:163], v155 offset:2048
	ds_read_b128 v[164:167], v155 offset:3072
	v_add_u32_e32 v155, s64, v150
	ds_read_b128 v[168:171], v155
	ds_read_b128 v[172:175], v155 offset:1024
	ds_read_b128 v[176:179], v155 offset:2048
	ds_read_b128 v[180:183], v155 offset:3072
	s_mov_b64 s[100:101], s[38:39]
	s_add_u32 s38, s38, 0x80000
	s_addc_u32 s39, s39, 0
	ds_read_b128 v[184:187], v153 offset:32768
	ds_read_b128 v[188:191], v153 offset:33792
	ds_read_b128 v[192:195], v153 offset:34816
	ds_read_b128 v[196:199], v153 offset:35840
	ds_read_b128 v[200:203], v153 offset:36864
	ds_read_b128 v[204:207], v153 offset:37888
	ds_read_b128 v[208:211], v153 offset:38912
	ds_read_b128 v[212:215], v153 offset:39936
	s_mov_b32 m0, s6
	s_nop 0
	global_load_lds_dwordx4 v134, s[100:101]
	s_mov_b32 m0, s7
	s_nop 0
	global_load_lds_dwordx4 v130, s[100:101]
	s_mov_b32 m0, s41
	s_nop 0
	global_load_lds_dwordx4 v134, s[38:39]
	s_mov_b32 m0, s42
	s_nop 0
	global_load_lds_dwordx4 v130, s[38:39]
	s_waitcnt vmcnt(8)
	s_waitcnt lgkmcnt(0)
	s_barrier
	s_setprio 1
	v_mfma_f32_16x16x32_bf16 v[124:127], v[144:147], v[184:187], v[124:127]
	v_mfma_f32_16x16x32_bf16 v[116:119], v[160:163], v[184:187], v[116:119]
	v_mfma_f32_16x16x32_bf16 v[108:111], v[144:147], v[192:195], v[108:111]
	v_mfma_f32_16x16x32_bf16 v[100:103], v[160:163], v[192:195], v[100:103]
	v_mfma_f32_16x16x32_bf16 v[92:95], v[144:147], v[200:203], v[92:95]
	v_mfma_f32_16x16x32_bf16 v[84:87], v[160:163], v[200:203], v[84:87]
	v_mfma_f32_16x16x32_bf16 v[76:79], v[144:147], v[208:211], v[76:79]
	v_mfma_f32_16x16x32_bf16 v[68:71], v[160:163], v[208:211], v[68:71]
	v_mfma_f32_16x16x32_bf16 v[124:127], v[156:159], v[188:191], v[124:127]
	v_mfma_f32_16x16x32_bf16 v[116:119], v[164:167], v[188:191], v[116:119]
	v_mfma_f32_16x16x32_bf16 v[108:111], v[156:159], v[196:199], v[108:111]
	v_mfma_f32_16x16x32_bf16 v[100:103], v[164:167], v[196:199], v[100:103]
	v_mfma_f32_16x16x32_bf16 v[92:95], v[156:159], v[204:207], v[92:95]
	v_mfma_f32_16x16x32_bf16 v[84:87], v[164:167], v[204:207], v[84:87]
	v_mfma_f32_16x16x32_bf16 v[76:79], v[156:159], v[212:215], v[76:79]
	v_mfma_f32_16x16x32_bf16 v[68:71], v[164:167], v[212:215], v[68:71]
	s_setprio 0
	s_setprio 1
	v_mfma_f32_16x16x32_bf16 v[120:123], v[168:171], v[184:187], v[120:123]
	v_mfma_f32_16x16x32_bf16 v[112:115], v[176:179], v[184:187], v[112:115]
	v_mfma_f32_16x16x32_bf16 v[104:107], v[168:171], v[192:195], v[104:107]
	v_mfma_f32_16x16x32_bf16 v[96:99], v[176:179], v[192:195], v[96:99]
	v_mfma_f32_16x16x32_bf16 v[88:91], v[168:171], v[200:203], v[88:91]
	v_mfma_f32_16x16x32_bf16 v[80:83], v[176:179], v[200:203], v[80:83]
	v_mfma_f32_16x16x32_bf16 v[72:75], v[168:171], v[208:211], v[72:75]
	v_mfma_f32_16x16x32_bf16 v[64:67], v[176:179], v[208:211], v[64:67]
	v_mfma_f32_16x16x32_bf16 v[120:123], v[172:175], v[188:191], v[120:123]
	v_mfma_f32_16x16x32_bf16 v[112:115], v[180:183], v[188:191], v[112:115]
	v_mfma_f32_16x16x32_bf16 v[104:107], v[172:175], v[196:199], v[104:107]
	v_mfma_f32_16x16x32_bf16 v[96:99], v[180:183], v[196:199], v[96:99]
	v_mfma_f32_16x16x32_bf16 v[88:91], v[172:175], v[204:207], v[88:91]
	v_mfma_f32_16x16x32_bf16 v[80:83], v[180:183], v[204:207], v[80:83]
	v_mfma_f32_16x16x32_bf16 v[72:75], v[172:175], v[212:215], v[72:75]
	v_mfma_f32_16x16x32_bf16 v[64:67], v[180:183], v[212:215], v[64:67]
	s_setprio 0
	s_barrier
	s_add_i32 s38, s63, s4
	s_add_u32 s98, s34, 0x80
	s_addc_u32 s99, s35, 0
	s_mov_b32 m0, s38
	ds_read_b128 v[184:187], v153 offset:49152
	ds_read_b128 v[188:191], v153 offset:50176
	ds_read_b128 v[192:195], v153 offset:51200
	ds_read_b128 v[196:199], v153 offset:52224
	ds_read_b128 v[200:203], v153 offset:53248
	ds_read_b128 v[204:207], v153 offset:54272
	ds_read_b128 v[208:211], v153 offset:55296
	ds_read_b128 v[212:215], v153 offset:56320
	global_load_lds_dwordx4 v132, s[98:99]
	s_add_i32 m0, s38, 0x2000
	s_add_u32 s34, s34, 0x80080
	s_addc_u32 s35, s35, 0
	s_add_i32 s38, s64, s4
	global_load_lds_dwordx4 v128, s[98:99]
	s_mov_b32 m0, s38
	s_nop 0
	global_load_lds_dwordx4 v132, s[34:35]
	s_add_i32 m0, s38, 0x2000
	s_nop 0
	global_load_lds_dwordx4 v128, s[34:35]
	s_waitcnt vmcnt(6)
	s_waitcnt lgkmcnt(0)
	s_barrier
	s_setprio 1
	v_mfma_f32_16x16x32_bf16 v[60:63], v[144:147], v[184:187], v[60:63]
	v_mfma_f32_16x16x32_bf16 v[52:55], v[160:163], v[184:187], v[52:55]
	v_mfma_f32_16x16x32_bf16 v[44:47], v[144:147], v[192:195], v[44:47]
	v_mfma_f32_16x16x32_bf16 v[36:39], v[160:163], v[192:195], v[36:39]
	v_mfma_f32_16x16x32_bf16 v[28:31], v[144:147], v[200:203], v[28:31]
	v_mfma_f32_16x16x32_bf16 v[20:23], v[160:163], v[200:203], v[20:23]
	v_mfma_f32_16x16x32_bf16 v[12:15], v[144:147], v[208:211], v[12:15]
	v_mfma_f32_16x16x32_bf16 v[4:7], v[160:163], v[208:211], v[4:7]
	v_mfma_f32_16x16x32_bf16 v[60:63], v[156:159], v[188:191], v[60:63]
	v_mfma_f32_16x16x32_bf16 v[52:55], v[164:167], v[188:191], v[52:55]
	v_mfma_f32_16x16x32_bf16 v[44:47], v[156:159], v[196:199], v[44:47]
	v_mfma_f32_16x16x32_bf16 v[36:39], v[164:167], v[196:199], v[36:39]
	v_mfma_f32_16x16x32_bf16 v[28:31], v[156:159], v[204:207], v[28:31]
	v_mfma_f32_16x16x32_bf16 v[20:23], v[164:167], v[204:207], v[20:23]
	v_mfma_f32_16x16x32_bf16 v[12:15], v[156:159], v[212:215], v[12:15]
	v_mfma_f32_16x16x32_bf16 v[4:7], v[164:167], v[212:215], v[4:7]
	s_setprio 0
	s_setprio 1
	v_mfma_f32_16x16x32_bf16 v[56:59], v[168:171], v[184:187], v[56:59]
	v_mfma_f32_16x16x32_bf16 v[48:51], v[176:179], v[184:187], v[48:51]
	v_mfma_f32_16x16x32_bf16 v[40:43], v[168:171], v[192:195], v[40:43]
	v_mfma_f32_16x16x32_bf16 v[32:35], v[176:179], v[192:195], v[32:35]
	v_mfma_f32_16x16x32_bf16 v[24:27], v[168:171], v[200:203], v[24:27]
	v_mfma_f32_16x16x32_bf16 v[16:19], v[176:179], v[200:203], v[16:19]
	v_mfma_f32_16x16x32_bf16 v[8:11], v[168:171], v[208:211], v[8:11]
	v_mfma_f32_16x16x32_bf16 v[0:3], v[176:179], v[208:211], v[0:3]
	v_mfma_f32_16x16x32_bf16 v[56:59], v[172:175], v[188:191], v[56:59]
	v_mfma_f32_16x16x32_bf16 v[48:51], v[180:183], v[188:191], v[48:51]
	v_mfma_f32_16x16x32_bf16 v[40:43], v[172:175], v[196:199], v[40:43]
	v_mfma_f32_16x16x32_bf16 v[32:35], v[180:183], v[196:199], v[32:35]
	v_mfma_f32_16x16x32_bf16 v[24:27], v[172:175], v[204:207], v[24:27]
	v_mfma_f32_16x16x32_bf16 v[16:19], v[180:183], v[204:207], v[16:19]
	v_mfma_f32_16x16x32_bf16 v[8:11], v[172:175], v[212:215], v[8:11]
	v_mfma_f32_16x16x32_bf16 v[0:3], v[180:183], v[212:215], v[0:3]
	s_setprio 0
	s_barrier
	s_add_i32 s62, s62, 2
	s_add_u32 s30, s30, 0x100
	s_addc_u32 s31, s31, 0
	s_add_u32 s60, s60, 0x100
	s_addc_u32 s61, s61, 0
	s_cmp_gt_u32 s62, 29
	s_cbranch_scc0 .LBB0_1824

; #define PG8_STAGE(bufoff, gbase, voff) do { _Pragma("unroll") for (int _i = 0; _i < 2; ++_i) \
;         __builtin_amdgcn_global_load_lds((const unsigned*)((const char*)(gbase) + (voff)[_i]), (PG8_LAS unsigned*)(lds + (bufoff) + ldsw + _i * 8192), 16, 0, 0); } while (0)
; #define PG8_LDA(dst, b, h) do { _Pragma("unroll") for (int m = 0; m < 4; ++m) _Pragma("unroll") for (int k = 0; k < 2; ++k) dst[m][k] = *(const PG8_LAS bf16x8*)(lds + PG8_SA(b, h) + aoff + m * 2048 + k * 1024); } while (0)
; #define PG8_LDB(dst, b, h) do { _Pragma("unroll") for (int n = 0; n < 2; ++n) _Pragma("unroll") for (int k = 0; k < 2; ++k) dst[n][k] = *(const PG8_LAS bf16x8*)(lds + PG8_SB(b, h) + boff + n * 2048 + k * 1024); } while (0)
; #define PG8_MMA(ai, bj, At, Bt) do { __builtin_amdgcn_s_setprio(1); _Pragma("unroll") for (int m = 0; m < 4; ++m) _Pragma("unroll") for (int n = 0; n < 2; ++n) _Pragma("unroll") for (int k = 0; k < 2; ++k) \
;         acc[ai][bj][m][n] = __builtin_amdgcn_mfma_f32_16x16x32_bf16(Bt[n][k], At[m][k], acc[ai][bj][m][n], 0, 0, 0); __builtin_amdgcn_s_setprio(0); } while (0)
; #define PG8_WAIT_V(n) asm volatile("s_waitcnt vmcnt(" #n ")" ::: "memory")
; template <class Epi, class Sched, bool ALIGN_EPI = false, bool SP2 = false>
; __device__ __forceinline__ void gemm_phase(PG8_LAS unsigned char* lds, const Gemm g, const Sched& S, const Epi& E) {
;     ...
;             const bool last = (t == nt - 2);
;             if constexpr (Epi::HAS_MID) { if (t == E.mid_t) E.mid(acc, cur, wr, wc, fr, fq); }
;             const char* a1 = cA + (size_t)(t + 1) * kstep;
;             const char* a2 = last ? nA : cA + (size_t)(t + 2) * kstep; const char* b2 = last ? nB : cB + (size_t)(t + 2) * kstep;
;             const char* a3 = a2 + kstep; const char* b3 = b2 + kstep;
;             if (last && has_next) S.a_ready(nxt);
;             if constexpr (SP2) {
;             PG8_LDB(B0, 0, 0); PG8_LDB(B1, 0, 1); PG8_SCHED; PG8_LDA(At, 0, 0); PG8_STAGE(PG8_SA(1, 1), a1 + hstepA, voffA);
;             PG8_WAIT_V(8); PG8_WAIT_L(0); PG8_BAR; PG8_MMA(0, 0, At, B0); PG8_MMA(0, 1, At, B1); PG8_BAR; PG8_SCHED;
;             PG8_LDA(At, 0, 1); PG8_STAGE(PG8_SB(0, 0), b2, voffB); PG8_STAGE(PG8_SB(0, 1), b2 + hstepB, voffB); PG8_STAGE(PG8_SA(0, 0), a2, voffA);
;             PG8_WAIT_V(8); PG8_WAIT_L(0); PG8_BAR; PG8_MMA(1, 0, At, B0); PG8_MMA(1, 1, At, B1); PG8_BAR; PG8_SCHED;
.LBB0_1912:
	ds_read_b128 v[144:147], v151
	ds_read_b128 v[154:157], v151 offset:1024
	ds_read_b128 v[158:161], v151 offset:2048
	ds_read_b128 v[162:165], v151 offset:3072
	ds_read_b128 v[166:169], v152
	ds_read_b128 v[170:173], v152 offset:1024
	ds_read_b128 v[174:177], v152 offset:2048
	ds_read_b128 v[178:181], v152 offset:3072
	s_add_u32 s4, s40, 0x100
	s_addc_u32 s5, s41, 0
	s_cmpk_eq_i32 s65, 0x54
	s_cselect_b32 s47, s35, s5
	s_cselect_b32 s46, s34, s4
	s_cselect_b32 s43, s37, s64
	s_cselect_b32 s42, s36, s39
	ds_read_b128 v[182:185], v153
	ds_read_b128 v[186:189], v153 offset:1024
	ds_read_b128 v[190:193], v153 offset:2048
	ds_read_b128 v[194:197], v153 offset:3072
	ds_read_b128 v[198:201], v153 offset:4096
	ds_read_b128 v[202:205], v153 offset:5120
	ds_read_b128 v[206:209], v153 offset:6144
	ds_read_b128 v[210:213], v153 offset:7168
	s_add_u32 s98, s40, 0x80
	s_addc_u32 s99, s41, 0
	s_mov_b32 m0, s55
	s_nop 0
	global_load_lds_dwordx4 v128, s[98:99]
	s_mov_b32 m0, s56
	s_nop 0
	global_load_lds_dwordx4 v132, s[98:99]
	s_add_i32 m0, s50, 0xc000
	s_nop 0
	global_load_lds_dwordx4 v136, s[40:41]
	s_add_i32 m0, s50, 0xe000
	s_nop 0
	global_load_lds_dwordx4 v138, s[40:41]
	s_waitcnt vmcnt(8)
	s_waitcnt lgkmcnt(0)
	s_barrier
	s_setprio 1
	v_mfma_f32_16x16x32_bf16 v[120:123], v[144:147], v[182:185], v[120:123]
	v_mfma_f32_16x16x32_bf16 v[124:127], v[158:161], v[182:185], v[124:127]
	v_mfma_f32_16x16x32_bf16 v[104:107], v[144:147], v[190:193], v[104:107]
	v_mfma_f32_16x16x32_bf16 v[108:111], v[158:161], v[190:193], v[108:111]
	v_mfma_f32_16x16x32_bf16 v[88:91], v[144:147], v[198:201], v[88:91]
	v_mfma_f32_16x16x32_bf16 v[92:95], v[158:161], v[198:201], v[92:95]
	v_mfma_f32_16x16x32_bf16 v[72:75], v[144:147], v[206:209], v[72:75]
	v_mfma_f32_16x16x32_bf16 v[76:79], v[158:161], v[206:209], v[76:79]
	v_mfma_f32_16x16x32_bf16 v[120:123], v[154:157], v[186:189], v[120:123]
	v_mfma_f32_16x16x32_bf16 v[124:127], v[162:165], v[186:189], v[124:127]
	v_mfma_f32_16x16x32_bf16 v[104:107], v[154:157], v[194:197], v[104:107]
	v_mfma_f32_16x16x32_bf16 v[108:111], v[162:165], v[194:197], v[108:111]
	v_mfma_f32_16x16x32_bf16 v[88:91], v[154:157], v[202:205], v[88:91]
	v_mfma_f32_16x16x32_bf16 v[92:95], v[162:165], v[202:205], v[92:95]
	v_mfma_f32_16x16x32_bf16 v[72:75], v[154:157], v[210:213], v[72:75]
	v_mfma_f32_16x16x32_bf16 v[76:79], v[162:165], v[210:213], v[76:79]
	s_setprio 0
	s_setprio 1
	v_mfma_f32_16x16x32_bf16 v[112:115], v[166:169], v[182:185], v[112:115]
	v_mfma_f32_16x16x32_bf16 v[116:119], v[174:177], v[182:185], v[116:119]
	v_mfma_f32_16x16x32_bf16 v[96:99], v[166:169], v[190:193], v[96:99]
	v_mfma_f32_16x16x32_bf16 v[100:103], v[174:177], v[190:193], v[100:103]
	v_mfma_f32_16x16x32_bf16 v[80:83], v[166:169], v[198:201], v[80:83]
	v_mfma_f32_16x16x32_bf16 v[84:87], v[174:177], v[198:201], v[84:87]
	v_mfma_f32_16x16x32_bf16 v[64:67], v[166:169], v[206:209], v[64:67]
	v_mfma_f32_16x16x32_bf16 v[68:71], v[174:177], v[206:209], v[68:71]
	v_mfma_f32_16x16x32_bf16 v[112:115], v[170:173], v[186:189], v[112:115]
	v_mfma_f32_16x16x32_bf16 v[116:119], v[178:181], v[186:189], v[116:119]
	v_mfma_f32_16x16x32_bf16 v[96:99], v[170:173], v[194:197], v[96:99]
	v_mfma_f32_16x16x32_bf16 v[100:103], v[178:181], v[194:197], v[100:103]
	v_mfma_f32_16x16x32_bf16 v[80:83], v[170:173], v[202:205], v[80:83]
	v_mfma_f32_16x16x32_bf16 v[84:87], v[178:181], v[202:205], v[84:87]
	v_mfma_f32_16x16x32_bf16 v[64:67], v[170:173], v[210:213], v[64:67]
	v_mfma_f32_16x16x32_bf16 v[68:71], v[178:181], v[210:213], v[68:71]
	s_setprio 0
	s_barrier
	s_add_i32 s40, s58, s33
	s_mov_b32 m0, s40
	ds_read_b128 v[182:185], v153 offset:16384
	ds_read_b128 v[186:189], v153 offset:17408
	ds_read_b128 v[190:193], v153 offset:18432
	ds_read_b128 v[194:197], v153 offset:19456
	ds_read_b128 v[198:201], v153 offset:20480
	ds_read_b128 v[202:205], v153 offset:21504
	ds_read_b128 v[206:209], v153 offset:22528
	ds_read_b128 v[210:213], v153 offset:23552
	global_load_lds_dwordx4 v130, s[42:43]
	s_add_i32 m0, s40, 0x2000
	s_add_u32 s40, s42, 0x160000
	s_addc_u32 s41, s43, 0
	s_add_i32 s66, s59, s33
	global_load_lds_dwordx4 v134, s[42:43]
	s_mov_b32 m0, s66
	s_nop 0
	global_load_lds_dwordx4 v130, s[40:41]
	s_add_i32 m0, s66, 0x2000
	s_nop 0
	global_load_lds_dwordx4 v134, s[40:41]
	s_waitcnt vmcnt(6)
	s_waitcnt lgkmcnt(0)
	s_barrier
	s_setprio 1
	v_mfma_f32_16x16x32_bf16 v[56:59], v[144:147], v[182:185], v[56:59]
	v_mfma_f32_16x16x32_bf16 v[60:63], v[158:161], v[182:185], v[60:63]
	v_mfma_f32_16x16x32_bf16 v[40:43], v[144:147], v[190:193], v[40:43]
	v_mfma_f32_16x16x32_bf16 v[44:47], v[158:161], v[190:193], v[44:47]
	v_mfma_f32_16x16x32_bf16 v[24:27], v[144:147], v[198:201], v[24:27]
	v_mfma_f32_16x16x32_bf16 v[28:31], v[158:161], v[198:201], v[28:31]
	v_mfma_f32_16x16x32_bf16 v[8:11], v[144:147], v[206:209], v[8:11]
	v_mfma_f32_16x16x32_bf16 v[12:15], v[158:161], v[206:209], v[12:15]
	v_mfma_f32_16x16x32_bf16 v[56:59], v[154:157], v[186:189], v[56:59]
	v_mfma_f32_16x16x32_bf16 v[60:63], v[162:165], v[186:189], v[60:63]
	v_mfma_f32_16x16x32_bf16 v[40:43], v[154:157], v[194:197], v[40:43]
	v_mfma_f32_16x16x32_bf16 v[44:47], v[162:165], v[194:197], v[44:47]
	v_mfma_f32_16x16x32_bf16 v[24:27], v[154:157], v[202:205], v[24:27]
	v_mfma_f32_16x16x32_bf16 v[28:31], v[162:165], v[202:205], v[28:31]
	v_mfma_f32_16x16x32_bf16 v[8:11], v[154:157], v[210:213], v[8:11]
	v_mfma_f32_16x16x32_bf16 v[12:15], v[162:165], v[210:213], v[12:15]
	s_setprio 0
	s_setprio 1
	v_mfma_f32_16x16x32_bf16 v[48:51], v[166:169], v[182:185], v[48:51]
	v_mfma_f32_16x16x32_bf16 v[52:55], v[174:177], v[182:185], v[52:55]
	v_mfma_f32_16x16x32_bf16 v[32:35], v[166:169], v[190:193], v[32:35]
	v_mfma_f32_16x16x32_bf16 v[36:39], v[174:177], v[190:193], v[36:39]
	v_mfma_f32_16x16x32_bf16 v[16:19], v[166:169], v[198:201], v[16:19]
	v_mfma_f32_16x16x32_bf16 v[20:23], v[174:177], v[198:201], v[20:23]
	v_mfma_f32_16x16x32_bf16 v[4:7], v[166:169], v[206:209], v[4:7]
	v_mfma_f32_16x16x32_bf16 v[0:3], v[174:177], v[206:209], v[0:3]
	v_mfma_f32_16x16x32_bf16 v[48:51], v[170:173], v[186:189], v[48:51]
	v_mfma_f32_16x16x32_bf16 v[52:55], v[178:181], v[186:189], v[52:55]
	v_mfma_f32_16x16x32_bf16 v[32:35], v[170:173], v[194:197], v[32:35]
	v_mfma_f32_16x16x32_bf16 v[36:39], v[178:181], v[194:197], v[36:39]
	v_mfma_f32_16x16x32_bf16 v[16:19], v[170:173], v[202:205], v[16:19]
	v_mfma_f32_16x16x32_bf16 v[20:23], v[178:181], v[202:205], v[20:23]
	v_mfma_f32_16x16x32_bf16 v[4:7], v[170:173], v[210:213], v[4:7]
	v_mfma_f32_16x16x32_bf16 v[0:3], v[178:181], v[210:213], v[0:3]
	s_setprio 0
	s_barrier
; #define PG8_STAGE(bufoff, gbase, voff) do { _Pragma("unroll") for (int _i = 0; _i < 2; ++_i) \
;         __builtin_amdgcn_global_load_lds((const unsigned*)((const char*)(gbase) + (voff)[_i]), (PG8_LAS unsigned*)(lds + (bufoff) + ldsw + _i * 8192), 16, 0, 0); } while (0)
; #define PG8_LDA(dst, b, h) do { _Pragma("unroll") for (int m = 0; m < 4; ++m) _Pragma("unroll") for (int k = 0; k < 2; ++k) dst[m][k] = *(const PG8_LAS bf16x8*)(lds + PG8_SA(b, h) + aoff + m * 2048 + k * 1024); } while (0)
; #define PG8_LDB(dst, b, h) do { _Pragma("unroll") for (int n = 0; n < 2; ++n) _Pragma("unroll") for (int k = 0; k < 2; ++k) dst[n][k] = *(const PG8_LAS bf16x8*)(lds + PG8_SB(b, h) + boff + n * 2048 + k * 1024); } while (0)
; #define PG8_MMA(ai, bj, At, Bt) do { __builtin_amdgcn_s_setprio(1); _Pragma("unroll") for (int m = 0; m < 4; ++m) _Pragma("unroll") for (int n = 0; n < 2; ++n) _Pragma("unroll") for (int k = 0; k < 2; ++k) \
;         acc[ai][bj][m][n] = __builtin_amdgcn_mfma_f32_16x16x32_bf16(Bt[n][k], At[m][k], acc[ai][bj][m][n], 0, 0, 0); __builtin_amdgcn_s_setprio(0); } while (0)
; #define PG8_WAIT_V(n) asm volatile("s_waitcnt vmcnt(" #n ")" ::: "memory")
; #define PG8_WAIT_L(n) asm volatile("s_waitcnt lgkmcnt(" #n ")" ::: "memory")
; #define PG8_BAR __builtin_amdgcn_s_barrier()
; #define PG8_SCHED __builtin_amdgcn_sched_barrier(0)
; template <class Epi, class Sched, bool ALIGN_EPI = false, bool SP2 = false>
; __device__ __forceinline__ void gemm_phase(PG8_LAS unsigned char* lds, const Gemm g, const Sched& S, const Epi& E) {
;     ...
;             PG8_LDB(B0, 1, 0); PG8_LDB(B1, 1, 1); PG8_SCHED; PG8_LDA(At, 1, 0); PG8_STAGE(PG8_SA(0, 1), a2 + hstepA, voffA);
;             PG8_WAIT_V(8); PG8_WAIT_L(0); PG8_BAR; PG8_MMA(0, 0, At, B0); PG8_MMA(0, 1, At, B1); PG8_BAR; PG8_SCHED;
;             PG8_LDA(At, 1, 1); PG8_STAGE(PG8_SB(1, 0), b3, voffB); PG8_STAGE(PG8_SB(1, 1), b3 + hstepB, voffB); PG8_STAGE(PG8_SA(1, 0), a3, voffA);
;             PG8_WAIT_V(8); PG8_WAIT_L(0); PG8_BAR; PG8_MMA(1, 0, At, B0); PG8_MMA(1, 1, At, B1); PG8_BAR; PG8_SCHED;
;     ...
;         if constexpr (ALIGN_EPI) { if (wr == 0) PG8_BAR; }
	s_add_i32 s66, 0, 0x18000
	s_add_i32 s67, 0, 0x1c000
	v_add_u32_e32 v162, s66, v150
	v_add_u32_e32 v178, s67, v150
	ds_read_b128 v[144:147], v162
	ds_read_b128 v[154:157], v162 offset:1024
	ds_read_b128 v[158:161], v162 offset:2048
	ds_read_b128 v[162:165], v162 offset:3072
	ds_read_b128 v[166:169], v178
	ds_read_b128 v[170:173], v178 offset:1024
	ds_read_b128 v[174:177], v178 offset:2048
	ds_read_b128 v[178:181], v178 offset:3072
	s_add_u32 s40, s46, 0x160000
	s_addc_u32 s41, s47, 0
	ds_read_b128 v[182:185], v153 offset:32768
	ds_read_b128 v[186:189], v153 offset:33792
	ds_read_b128 v[190:193], v153 offset:34816
	ds_read_b128 v[194:197], v153 offset:35840
	ds_read_b128 v[198:201], v153 offset:36864
	ds_read_b128 v[202:205], v153 offset:37888
	ds_read_b128 v[206:209], v153 offset:38912
	ds_read_b128 v[210:213], v153 offset:39936
	s_mov_b32 m0, s50
	s_nop 0
	global_load_lds_dwordx4 v128, s[46:47]
	s_mov_b32 m0, s51
	s_nop 0
	global_load_lds_dwordx4 v132, s[46:47]
	s_mov_b32 m0, s52
	s_nop 0
	global_load_lds_dwordx4 v128, s[40:41]
	s_mov_b32 m0, s53
	s_nop 0
	global_load_lds_dwordx4 v132, s[40:41]
	s_waitcnt vmcnt(8)
	s_waitcnt lgkmcnt(0)
	s_barrier
	s_setprio 1
	v_mfma_f32_16x16x32_bf16 v[120:123], v[144:147], v[182:185], v[120:123]
	v_mfma_f32_16x16x32_bf16 v[124:127], v[158:161], v[182:185], v[124:127]
	v_mfma_f32_16x16x32_bf16 v[104:107], v[144:147], v[190:193], v[104:107]
	v_mfma_f32_16x16x32_bf16 v[108:111], v[158:161], v[190:193], v[108:111]
	v_mfma_f32_16x16x32_bf16 v[88:91], v[144:147], v[198:201], v[88:91]
	v_mfma_f32_16x16x32_bf16 v[92:95], v[158:161], v[198:201], v[92:95]
	v_mfma_f32_16x16x32_bf16 v[72:75], v[144:147], v[206:209], v[72:75]
	v_mfma_f32_16x16x32_bf16 v[76:79], v[158:161], v[206:209], v[76:79]
	v_mfma_f32_16x16x32_bf16 v[120:123], v[154:157], v[186:189], v[120:123]
	v_mfma_f32_16x16x32_bf16 v[124:127], v[162:165], v[186:189], v[124:127]
	v_mfma_f32_16x16x32_bf16 v[104:107], v[154:157], v[194:197], v[104:107]
	v_mfma_f32_16x16x32_bf16 v[108:111], v[162:165], v[194:197], v[108:111]
	v_mfma_f32_16x16x32_bf16 v[88:91], v[154:157], v[202:205], v[88:91]
	v_mfma_f32_16x16x32_bf16 v[92:95], v[162:165], v[202:205], v[92:95]
	v_mfma_f32_16x16x32_bf16 v[72:75], v[154:157], v[210:213], v[72:75]
	v_mfma_f32_16x16x32_bf16 v[76:79], v[162:165], v[210:213], v[76:79]
	s_setprio 0
	s_setprio 1
	v_mfma_f32_16x16x32_bf16 v[112:115], v[166:169], v[182:185], v[112:115]
	v_mfma_f32_16x16x32_bf16 v[116:119], v[174:177], v[182:185], v[116:119]
	v_mfma_f32_16x16x32_bf16 v[96:99], v[166:169], v[190:193], v[96:99]
	v_mfma_f32_16x16x32_bf16 v[100:103], v[174:177], v[190:193], v[100:103]
	v_mfma_f32_16x16x32_bf16 v[80:83], v[166:169], v[198:201], v[80:83]
	v_mfma_f32_16x16x32_bf16 v[84:87], v[174:177], v[198:201], v[84:87]
	v_mfma_f32_16x16x32_bf16 v[64:67], v[166:169], v[206:209], v[64:67]
	v_mfma_f32_16x16x32_bf16 v[68:71], v[174:177], v[206:209], v[68:71]
	v_mfma_f32_16x16x32_bf16 v[112:115], v[170:173], v[186:189], v[112:115]
	v_mfma_f32_16x16x32_bf16 v[116:119], v[178:181], v[186:189], v[116:119]
	v_mfma_f32_16x16x32_bf16 v[96:99], v[170:173], v[194:197], v[96:99]
	v_mfma_f32_16x16x32_bf16 v[100:103], v[178:181], v[194:197], v[100:103]
	v_mfma_f32_16x16x32_bf16 v[80:83], v[170:173], v[202:205], v[80:83]
	v_mfma_f32_16x16x32_bf16 v[84:87], v[178:181], v[202:205], v[84:87]
	v_mfma_f32_16x16x32_bf16 v[64:67], v[170:173], v[210:213], v[64:67]
	v_mfma_f32_16x16x32_bf16 v[68:71], v[178:181], v[210:213], v[68:71]
	s_setprio 0
	s_barrier
	s_add_i32 s40, s66, s33
	s_add_u32 s98, s42, 0x80
	s_addc_u32 s99, s43, 0
	s_mov_b32 m0, s40
	ds_read_b128 v[182:185], v153 offset:49152
	ds_read_b128 v[186:189], v153 offset:50176
	ds_read_b128 v[190:193], v153 offset:51200
	ds_read_b128 v[194:197], v153 offset:52224
	ds_read_b128 v[198:201], v153 offset:53248
	ds_read_b128 v[202:205], v153 offset:54272
	ds_read_b128 v[206:209], v153 offset:55296
	ds_read_b128 v[210:213], v153 offset:56320
	global_load_lds_dwordx4 v130, s[98:99]
	s_add_i32 m0, s40, 0x2000
	s_add_u32 s40, s42, 0x160080
	s_addc_u32 s41, s43, 0
	s_add_i32 s42, s67, s33
	global_load_lds_dwordx4 v134, s[98:99]
	s_mov_b32 m0, s42
	s_nop 0
	global_load_lds_dwordx4 v130, s[40:41]
	s_add_i32 m0, s42, 0x2000
	s_nop 0
	global_load_lds_dwordx4 v134, s[40:41]
	s_waitcnt vmcnt(6)
	s_waitcnt lgkmcnt(0)
	s_barrier
	s_setprio 1
	v_mfma_f32_16x16x32_bf16 v[56:59], v[144:147], v[182:185], v[56:59]
	v_mfma_f32_16x16x32_bf16 v[60:63], v[158:161], v[182:185], v[60:63]
	v_mfma_f32_16x16x32_bf16 v[40:43], v[144:147], v[190:193], v[40:43]
	v_mfma_f32_16x16x32_bf16 v[44:47], v[158:161], v[190:193], v[44:47]
	v_mfma_f32_16x16x32_bf16 v[24:27], v[144:147], v[198:201], v[24:27]
	v_mfma_f32_16x16x32_bf16 v[28:31], v[158:161], v[198:201], v[28:31]
	v_mfma_f32_16x16x32_bf16 v[8:11], v[144:147], v[206:209], v[8:11]
	v_mfma_f32_16x16x32_bf16 v[12:15], v[158:161], v[206:209], v[12:15]
	v_mfma_f32_16x16x32_bf16 v[56:59], v[154:157], v[186:189], v[56:59]
	v_mfma_f32_16x16x32_bf16 v[60:63], v[162:165], v[186:189], v[60:63]
	v_mfma_f32_16x16x32_bf16 v[40:43], v[154:157], v[194:197], v[40:43]
	v_mfma_f32_16x16x32_bf16 v[44:47], v[162:165], v[194:197], v[44:47]
	v_mfma_f32_16x16x32_bf16 v[24:27], v[154:157], v[202:205], v[24:27]
	v_mfma_f32_16x16x32_bf16 v[28:31], v[162:165], v[202:205], v[28:31]
	v_mfma_f32_16x16x32_bf16 v[8:11], v[154:157], v[210:213], v[8:11]
	v_mfma_f32_16x16x32_bf16 v[12:15], v[162:165], v[210:213], v[12:15]
	s_setprio 0
	s_setprio 1
	v_mfma_f32_16x16x32_bf16 v[48:51], v[166:169], v[182:185], v[48:51]
	v_mfma_f32_16x16x32_bf16 v[52:55], v[174:177], v[182:185], v[52:55]
	v_mfma_f32_16x16x32_bf16 v[32:35], v[166:169], v[190:193], v[32:35]
	v_mfma_f32_16x16x32_bf16 v[36:39], v[174:177], v[190:193], v[36:39]
	v_mfma_f32_16x16x32_bf16 v[16:19], v[166:169], v[198:201], v[16:19]
	v_mfma_f32_16x16x32_bf16 v[20:23], v[174:177], v[198:201], v[20:23]
	v_mfma_f32_16x16x32_bf16 v[4:7], v[166:169], v[206:209], v[4:7]
	v_mfma_f32_16x16x32_bf16 v[0:3], v[174:177], v[206:209], v[0:3]
	v_mfma_f32_16x16x32_bf16 v[48:51], v[170:173], v[186:189], v[48:51]
	v_mfma_f32_16x16x32_bf16 v[52:55], v[178:181], v[186:189], v[52:55]
	v_mfma_f32_16x16x32_bf16 v[32:35], v[170:173], v[194:197], v[32:35]
	v_mfma_f32_16x16x32_bf16 v[36:39], v[178:181], v[194:197], v[36:39]
	v_mfma_f32_16x16x32_bf16 v[16:19], v[170:173], v[202:205], v[16:19]
	v_mfma_f32_16x16x32_bf16 v[20:23], v[178:181], v[202:205], v[20:23]
	v_mfma_f32_16x16x32_bf16 v[4:7], v[170:173], v[210:213], v[4:7]
	v_mfma_f32_16x16x32_bf16 v[0:3], v[178:181], v[210:213], v[0:3]
	s_setprio 0
	s_barrier
	s_add_i32 s65, s65, 2
	s_add_u32 s39, s39, 0x100
	s_addc_u32 s64, s64, 0
	s_cmpk_gt_u32 s65, 0x55
	s_mov_b64 s[40:41], s[4:5]
	s_cbranch_scc0 .LBB0_1912
	s_and_b64 vcc, exec, s[14:15]
	s_cbranch_vccz .LBB0_1915
	s_barrier
